# GEMM loops: 8 phases of 16 MFMAs merged into 4 segments of 32 MFMAs (8 barriers per iteration instead of 16); fragment reads complete before each leading barrier
# speedup vs baseline: 1.0031x; 1.0031x over previous
.LBB0_37:
	s_add_i32 s69, s48, 2
	s_add_u32 s46, s0, 0x100
	s_addc_u32 s47, s1, 0
	s_add_i32 s70, 0, 0x10000
	v_add_u32_e32 v156, s70, v153
	ds_read_b128 v[140:143], v156
	ds_read_b128 v[144:147], v156 offset:1024
	ds_read_b128 v[148:151], v156 offset:2048
	ds_read_b128 v[168:171], v156 offset:3072
	s_cmp_eq_u32 s12, s48
	s_cselect_b32 s48, s44, s13
	s_cselect_b32 s51, s43, s47
	s_cselect_b32 s50, s42, s46
	s_cselect_b32 s49, s45, s68
	v_lshl_add_u64 v[156:157], s[0:1], 0, v[136:137]
	ds_read_b128 v[172:175], v155
	ds_read_b128 v[176:179], v155 offset:1024
	ds_read_b128 v[180:183], v155 offset:2048
	ds_read_b128 v[184:187], v155 offset:3072
	ds_read_b128 v[188:191], v155 offset:4096
	ds_read_b128 v[192:195], v155 offset:5120
	ds_read_b128 v[196:199], v155 offset:6144
	ds_read_b128 v[224:227], v155 offset:7168
	s_add_i32 m0, s53, 0xc000
	s_nop 0
	global_load_lds_dwordx4 v[156:157], off
	v_lshl_add_u64 v[156:157], s[0:1], 0, v[138:139]
	s_add_i32 m0, s53, 0xe000
	s_nop 0
	global_load_lds_dwordx4 v[156:157], off
	s_add_i32 s71, 0, 0x14000
	v_add_u32_e32 v156, s71, v153
	s_add_i32 s0, s70, s52
	ds_read_b128 v[228:231], v156
	ds_read_b128 v[232:235], v156 offset:1024
	ds_read_b128 v[236:239], v156 offset:2048
	ds_read_b128 v[240:243], v156 offset:3072
	s_waitcnt lgkmcnt(0)
	s_barrier
	v_mfma_f32_16x16x32_bf16 v[126:129], v[140:143], v[172:175], v[126:129]
	v_mfma_f32_16x16x32_bf16 v[122:125], v[148:151], v[172:175], v[122:125]
	v_mfma_f32_16x16x32_bf16 v[110:113], v[140:143], v[180:183], v[110:113]
	v_mfma_f32_16x16x32_bf16 v[106:109], v[148:151], v[180:183], v[106:109]
	v_mfma_f32_16x16x32_bf16 v[94:97], v[140:143], v[188:191], v[94:97]
	v_mfma_f32_16x16x32_bf16 v[90:93], v[148:151], v[188:191], v[90:93]
	v_mfma_f32_16x16x32_bf16 v[78:81], v[140:143], v[196:199], v[78:81]
	v_mfma_f32_16x16x32_bf16 v[74:77], v[148:151], v[196:199], v[74:77]
	v_mfma_f32_16x16x32_bf16 v[126:129], v[144:147], v[176:179], v[126:129]
	v_mfma_f32_16x16x32_bf16 v[122:125], v[168:171], v[176:179], v[122:125]
	v_mfma_f32_16x16x32_bf16 v[110:113], v[144:147], v[184:187], v[110:113]
	v_mfma_f32_16x16x32_bf16 v[106:109], v[168:171], v[184:187], v[106:109]
	v_mfma_f32_16x16x32_bf16 v[94:97], v[144:147], v[192:195], v[94:97]
	v_mfma_f32_16x16x32_bf16 v[90:93], v[168:171], v[192:195], v[90:93]
	v_mfma_f32_16x16x32_bf16 v[78:81], v[144:147], v[224:227], v[78:81]
	v_mfma_f32_16x16x32_bf16 v[74:77], v[168:171], v[224:227], v[74:77]
	v_mfma_f32_16x16x32_bf16 v[118:121], v[228:231], v[172:175], v[118:121]
	v_mfma_f32_16x16x32_bf16 v[114:117], v[236:239], v[172:175], v[114:117]
	v_mfma_f32_16x16x32_bf16 v[102:105], v[228:231], v[180:183], v[102:105]
	v_mfma_f32_16x16x32_bf16 v[98:101], v[236:239], v[180:183], v[98:101]
	v_mfma_f32_16x16x32_bf16 v[86:89], v[228:231], v[188:191], v[86:89]
	v_mfma_f32_16x16x32_bf16 v[82:85], v[236:239], v[188:191], v[82:85]
	v_mfma_f32_16x16x32_bf16 v[70:73], v[228:231], v[196:199], v[70:73]
	v_mfma_f32_16x16x32_bf16 v[66:69], v[236:239], v[196:199], v[66:69]
	v_mfma_f32_16x16x32_bf16 v[118:121], v[232:235], v[176:179], v[118:121]
	v_mfma_f32_16x16x32_bf16 v[114:117], v[240:243], v[176:179], v[114:117]
	v_mfma_f32_16x16x32_bf16 v[102:105], v[232:235], v[184:187], v[102:105]
	v_mfma_f32_16x16x32_bf16 v[98:101], v[240:243], v[184:187], v[98:101]
	v_mfma_f32_16x16x32_bf16 v[86:89], v[232:235], v[192:195], v[86:89]
	v_mfma_f32_16x16x32_bf16 v[82:85], v[240:243], v[192:195], v[82:85]
	v_mfma_f32_16x16x32_bf16 v[70:73], v[232:235], v[224:227], v[70:73]
	v_mfma_f32_16x16x32_bf16 v[66:69], v[240:243], v[224:227], v[66:69]
	s_barrier
	s_mov_b32 m0, s53
	s_add_u32 s78, s50, s94
	s_addc_u32 s79, s51, s95
	ds_read_b128 v[172:175], v155 offset:16384
	ds_read_b128 v[176:179], v155 offset:17408
	ds_read_b128 v[180:183], v155 offset:18432
	ds_read_b128 v[184:187], v155 offset:19456
	ds_read_b128 v[188:191], v155 offset:20480
	ds_read_b128 v[192:195], v155 offset:21504
	ds_read_b128 v[196:199], v155 offset:22528
	ds_read_b128 v[224:227], v155 offset:23552
	global_load_lds_dwordx4 v134, s[50:51]
	s_mov_b32 m0, s54
	s_nop 0
	global_load_lds_dwordx4 v132, s[50:51]
	s_add_u32 s76, s48, s94
	s_addc_u32 s77, s49, s95
	s_mov_b32 m0, s0
	s_nop 0
	global_load_lds_dwordx4 v0, s[48:49]
	s_add_i32 m0, s0, 0x2000
	s_nop 0
	global_load_lds_dwordx4 v130, s[48:49]
	s_add_u32 s0, s48, 0x160000
	s_addc_u32 s1, s49, 0
	s_add_i32 s70, s71, s52
	s_mov_b32 m0, s70
	s_nop 0
	global_load_lds_dwordx4 v0, s[0:1]
	s_add_i32 m0, s70, 0x2000
	s_nop 0
	global_load_lds_dwordx4 v130, s[0:1]
	s_waitcnt vmcnt(6) lgkmcnt(0)
	s_barrier
	v_mfma_f32_16x16x32_bf16 v[62:65], v[140:143], v[172:175], v[62:65]
	v_mfma_f32_16x16x32_bf16 v[58:61], v[148:151], v[172:175], v[58:61]
	v_mfma_f32_16x16x32_bf16 v[46:49], v[140:143], v[180:183], v[46:49]
	v_mfma_f32_16x16x32_bf16 v[42:45], v[148:151], v[180:183], v[42:45]
	v_mfma_f32_16x16x32_bf16 v[30:33], v[140:143], v[188:191], v[30:33]
	v_mfma_f32_16x16x32_bf16 v[26:29], v[148:151], v[188:191], v[26:29]
	v_mfma_f32_16x16x32_bf16 v[14:17], v[140:143], v[196:199], v[14:17]
	v_mfma_f32_16x16x32_bf16 v[10:13], v[148:151], v[196:199], v[10:13]
	v_mfma_f32_16x16x32_bf16 v[62:65], v[144:147], v[176:179], v[62:65]
	v_mfma_f32_16x16x32_bf16 v[58:61], v[168:171], v[176:179], v[58:61]
	v_mfma_f32_16x16x32_bf16 v[46:49], v[144:147], v[184:187], v[46:49]
	v_mfma_f32_16x16x32_bf16 v[42:45], v[168:171], v[184:187], v[42:45]
	v_mfma_f32_16x16x32_bf16 v[30:33], v[144:147], v[192:195], v[30:33]
	v_mfma_f32_16x16x32_bf16 v[26:29], v[168:171], v[192:195], v[26:29]
	v_mfma_f32_16x16x32_bf16 v[14:17], v[144:147], v[224:227], v[14:17]
	v_mfma_f32_16x16x32_bf16 v[10:13], v[168:171], v[224:227], v[10:13]
	v_mfma_f32_16x16x32_bf16 v[54:57], v[228:231], v[172:175], v[54:57]
	v_mfma_f32_16x16x32_bf16 v[50:53], v[236:239], v[172:175], v[50:53]
	v_mfma_f32_16x16x32_bf16 v[38:41], v[228:231], v[180:183], v[38:41]
	v_mfma_f32_16x16x32_bf16 v[34:37], v[236:239], v[180:183], v[34:37]
	v_mfma_f32_16x16x32_bf16 v[22:25], v[228:231], v[188:191], v[22:25]
	v_mfma_f32_16x16x32_bf16 v[18:21], v[236:239], v[188:191], v[18:21]
	v_mfma_f32_16x16x32_bf16 v[6:9], v[228:231], v[196:199], v[6:9]
	v_mfma_f32_16x16x32_bf16 v[2:5], v[236:239], v[196:199], v[2:5]
	v_mfma_f32_16x16x32_bf16 v[54:57], v[232:235], v[176:179], v[54:57]
	v_mfma_f32_16x16x32_bf16 v[50:53], v[240:243], v[176:179], v[50:53]
	v_mfma_f32_16x16x32_bf16 v[38:41], v[232:235], v[184:187], v[38:41]
	v_mfma_f32_16x16x32_bf16 v[34:37], v[240:243], v[184:187], v[34:37]
	v_mfma_f32_16x16x32_bf16 v[22:25], v[232:235], v[192:195], v[22:25]
	v_mfma_f32_16x16x32_bf16 v[18:21], v[240:243], v[192:195], v[18:21]
	v_mfma_f32_16x16x32_bf16 v[6:9], v[232:235], v[224:227], v[6:9]
	v_mfma_f32_16x16x32_bf16 v[2:5], v[240:243], v[224:227], v[2:5]
	s_barrier
	s_add_i32 s70, 0, 0x18000
	v_add_u32_e32 v161, s70, v153
	ds_read_b128 v[140:143], v161
	ds_read_b128 v[144:147], v161 offset:1024
	ds_read_b128 v[148:151], v161 offset:2048
	ds_read_b128 v[168:171], v161 offset:3072
	s_add_u32 s0, s50, 0x2c0000
	s_addc_u32 s1, s51, 0
	ds_read_b128 v[172:175], v155 offset:32768
	ds_read_b128 v[176:179], v155 offset:33792
	ds_read_b128 v[180:183], v155 offset:34816
	ds_read_b128 v[184:187], v155 offset:35840
	ds_read_b128 v[188:191], v155 offset:36864
	ds_read_b128 v[192:195], v155 offset:37888
	ds_read_b128 v[196:199], v155 offset:38912
	ds_read_b128 v[224:227], v155 offset:39936
	s_mov_b32 m0, s55
	s_nop 0
	global_load_lds_dwordx4 v134, s[0:1]
	s_mov_b32 m0, s56
	s_nop 0
	global_load_lds_dwordx4 v132, s[0:1]
	s_add_i32 s50, 0, 0x1c000
	s_add_i32 s0, s70, s52
	v_add_u32_e32 v161, s50, v153
	ds_read_b128 v[228:231], v161
	ds_read_b128 v[232:235], v161 offset:1024
	ds_read_b128 v[236:239], v161 offset:2048
	ds_read_b128 v[240:243], v161 offset:3072
	s_waitcnt lgkmcnt(0)
	s_barrier
	v_mfma_f32_16x16x32_bf16 v[126:129], v[140:143], v[172:175], v[126:129]
	v_mfma_f32_16x16x32_bf16 v[122:125], v[148:151], v[172:175], v[122:125]
	v_mfma_f32_16x16x32_bf16 v[110:113], v[140:143], v[180:183], v[110:113]
	v_mfma_f32_16x16x32_bf16 v[106:109], v[148:151], v[180:183], v[106:109]
	v_mfma_f32_16x16x32_bf16 v[94:97], v[140:143], v[188:191], v[94:97]
	v_mfma_f32_16x16x32_bf16 v[90:93], v[148:151], v[188:191], v[90:93]
	v_mfma_f32_16x16x32_bf16 v[78:81], v[140:143], v[196:199], v[78:81]
	v_mfma_f32_16x16x32_bf16 v[74:77], v[148:151], v[196:199], v[74:77]
	v_mfma_f32_16x16x32_bf16 v[126:129], v[144:147], v[176:179], v[126:129]
	v_mfma_f32_16x16x32_bf16 v[122:125], v[168:171], v[176:179], v[122:125]
	v_mfma_f32_16x16x32_bf16 v[110:113], v[144:147], v[184:187], v[110:113]
	v_mfma_f32_16x16x32_bf16 v[106:109], v[168:171], v[184:187], v[106:109]
	v_mfma_f32_16x16x32_bf16 v[94:97], v[144:147], v[192:195], v[94:97]
	v_mfma_f32_16x16x32_bf16 v[90:93], v[168:171], v[192:195], v[90:93]
	v_mfma_f32_16x16x32_bf16 v[78:81], v[144:147], v[224:227], v[78:81]
	v_mfma_f32_16x16x32_bf16 v[74:77], v[168:171], v[224:227], v[74:77]
	v_mfma_f32_16x16x32_bf16 v[118:121], v[228:231], v[172:175], v[118:121]
	v_mfma_f32_16x16x32_bf16 v[114:117], v[236:239], v[172:175], v[114:117]
	v_mfma_f32_16x16x32_bf16 v[102:105], v[228:231], v[180:183], v[102:105]
	v_mfma_f32_16x16x32_bf16 v[98:101], v[236:239], v[180:183], v[98:101]
	v_mfma_f32_16x16x32_bf16 v[86:89], v[228:231], v[188:191], v[86:89]
	v_mfma_f32_16x16x32_bf16 v[82:85], v[236:239], v[188:191], v[82:85]
	v_mfma_f32_16x16x32_bf16 v[70:73], v[228:231], v[196:199], v[70:73]
	v_mfma_f32_16x16x32_bf16 v[66:69], v[236:239], v[196:199], v[66:69]
	v_mfma_f32_16x16x32_bf16 v[118:121], v[232:235], v[176:179], v[118:121]
	v_mfma_f32_16x16x32_bf16 v[114:117], v[240:243], v[176:179], v[114:117]
	v_mfma_f32_16x16x32_bf16 v[102:105], v[232:235], v[184:187], v[102:105]
	v_mfma_f32_16x16x32_bf16 v[98:101], v[240:243], v[184:187], v[98:101]
	v_mfma_f32_16x16x32_bf16 v[86:89], v[232:235], v[192:195], v[86:89]
	v_mfma_f32_16x16x32_bf16 v[82:85], v[240:243], v[192:195], v[82:85]
	v_mfma_f32_16x16x32_bf16 v[70:73], v[232:235], v[224:227], v[70:73]
	v_mfma_f32_16x16x32_bf16 v[66:69], v[240:243], v[224:227], v[66:69]
	s_barrier
	s_mov_b32 m0, s57
	ds_read_b128 v[172:175], v155 offset:49152
	ds_read_b128 v[176:179], v155 offset:50176
	ds_read_b128 v[180:183], v155 offset:51200
	ds_read_b128 v[184:187], v155 offset:52224
	ds_read_b128 v[188:191], v155 offset:53248
	ds_read_b128 v[192:195], v155 offset:54272
	ds_read_b128 v[196:199], v155 offset:55296
	ds_read_b128 v[224:227], v155 offset:56320
	global_load_lds_dwordx4 v134, s[78:79]
	s_mov_b32 m0, s58
	s_nop 0
	global_load_lds_dwordx4 v132, s[78:79]
	s_mov_b32 m0, s0
	s_nop 0
	global_load_lds_dwordx4 v0, s[76:77]
	s_add_i32 m0, s0, 0x2000
	s_nop 0
	global_load_lds_dwordx4 v130, s[76:77]
	s_add_u32 s0, s48, 0x160080
	s_addc_u32 s1, s49, 0
	s_add_i32 s48, s50, s52
	s_mov_b32 m0, s48
	s_nop 0
	global_load_lds_dwordx4 v0, s[0:1]
	s_add_i32 m0, s48, 0x2000
	s_nop 0
	global_load_lds_dwordx4 v130, s[0:1]
	s_waitcnt vmcnt(6) lgkmcnt(0)
	s_barrier
	v_mfma_f32_16x16x32_bf16 v[62:65], v[140:143], v[172:175], v[62:65]
	v_mfma_f32_16x16x32_bf16 v[58:61], v[148:151], v[172:175], v[58:61]
	v_mfma_f32_16x16x32_bf16 v[46:49], v[140:143], v[180:183], v[46:49]
	v_mfma_f32_16x16x32_bf16 v[42:45], v[148:151], v[180:183], v[42:45]
	v_mfma_f32_16x16x32_bf16 v[30:33], v[140:143], v[188:191], v[30:33]
	v_mfma_f32_16x16x32_bf16 v[26:29], v[148:151], v[188:191], v[26:29]
	v_mfma_f32_16x16x32_bf16 v[14:17], v[140:143], v[196:199], v[14:17]
	v_mfma_f32_16x16x32_bf16 v[10:13], v[148:151], v[196:199], v[10:13]
	v_mfma_f32_16x16x32_bf16 v[62:65], v[144:147], v[176:179], v[62:65]
	v_mfma_f32_16x16x32_bf16 v[58:61], v[168:171], v[176:179], v[58:61]
	v_mfma_f32_16x16x32_bf16 v[46:49], v[144:147], v[184:187], v[46:49]
	v_mfma_f32_16x16x32_bf16 v[42:45], v[168:171], v[184:187], v[42:45]
	v_mfma_f32_16x16x32_bf16 v[30:33], v[144:147], v[192:195], v[30:33]
	v_mfma_f32_16x16x32_bf16 v[26:29], v[168:171], v[192:195], v[26:29]
	v_mfma_f32_16x16x32_bf16 v[14:17], v[144:147], v[224:227], v[14:17]
	v_mfma_f32_16x16x32_bf16 v[10:13], v[168:171], v[224:227], v[10:13]
	v_mfma_f32_16x16x32_bf16 v[54:57], v[228:231], v[172:175], v[54:57]
	v_mfma_f32_16x16x32_bf16 v[50:53], v[236:239], v[172:175], v[50:53]
	v_mfma_f32_16x16x32_bf16 v[38:41], v[228:231], v[180:183], v[38:41]
	v_mfma_f32_16x16x32_bf16 v[34:37], v[236:239], v[180:183], v[34:37]
	v_mfma_f32_16x16x32_bf16 v[22:25], v[228:231], v[188:191], v[22:25]
	v_mfma_f32_16x16x32_bf16 v[18:21], v[236:239], v[188:191], v[18:21]
	v_mfma_f32_16x16x32_bf16 v[6:9], v[228:231], v[196:199], v[6:9]
	v_mfma_f32_16x16x32_bf16 v[2:5], v[236:239], v[196:199], v[2:5]
	v_mfma_f32_16x16x32_bf16 v[54:57], v[232:235], v[176:179], v[54:57]
	v_mfma_f32_16x16x32_bf16 v[50:53], v[240:243], v[176:179], v[50:53]
	v_mfma_f32_16x16x32_bf16 v[38:41], v[232:235], v[184:187], v[38:41]
	v_mfma_f32_16x16x32_bf16 v[34:37], v[240:243], v[184:187], v[34:37]
	v_mfma_f32_16x16x32_bf16 v[22:25], v[232:235], v[192:195], v[22:25]
	v_mfma_f32_16x16x32_bf16 v[18:21], v[240:243], v[192:195], v[18:21]
	v_mfma_f32_16x16x32_bf16 v[6:9], v[232:235], v[224:227], v[6:9]
	v_mfma_f32_16x16x32_bf16 v[2:5], v[240:243], v[224:227], v[2:5]
	s_barrier
	s_add_u32 s13, s13, 0x100
	s_addc_u32 s68, s68, 0
	s_mov_b64 s[0:1], s[46:47]
	s_mov_b32 s48, s69
	s_cmp_ge_i32 s69, s39
	s_cbranch_scc0 .LBB0_37
	s_cmp_eq_u32 s65, 2
	s_cbranch_scc1 .Lepi10_orig
	v_readlane_b32 s90, v255, 17
	v_readlane_b32 s91, v255, 18
	v_readlane_b32 s96, v255, 19
	v_readlane_b32 s97, v255, 20
	v_lshl_or_b32 v156, s66, 8, v154
	v_lshlrev_b32_e32 v156, 2, v156
	v_lshl_add_u32 v157, v152, 13, v156
	s_lshl_b32 s72, s67, 21
	s_add_u32 s74, s22, s72
	s_addc_u32 s75, s23, 0
	s_add_u32 s76, s22, s72
	s_addc_u32 s77, s23, 0
	s_lshr_b32 s73, s67, 3
	s_mul_i32 s73, s73, 0xc000
	s_add_u32 s73, s73, 0xa000
	s_add_u32 s70, s90, s73
	s_addc_u32 s71, s91, 0
	global_load_dwordx4 v[140:143], v156, s[70:71]
	global_load_dwordx4 v[144:147], v156, s[70:71] offset:64
	global_load_dwordx4 v[148:151], v156, s[70:71] offset:512
	global_load_dwordx4 v[168:171], v156, s[70:71] offset:576
	global_load_dwordx4 v[224:227], v157, s[74:75] nt
	global_load_dwordx4 v[228:231], v157, s[74:75] offset:64 nt
	global_load_dwordx4 v[232:235], v157, s[74:75] offset:512 nt
	global_load_dwordx4 v[236:239], v157, s[74:75] offset:576 nt
	s_add_u32 s74, s74, 0x20000
	s_addc_u32 s75, s75, 0
	global_load_dwordx4 v[240:243], v157, s[74:75] nt
	global_load_dwordx4 v[244:247], v157, s[74:75] offset:64 nt
	s_waitcnt vmcnt(5)
	v_pk_fma_f32 v[128:129], v[128:129], v[142:143], v[226:227]
	v_pk_fma_f32 v[126:127], v[126:127], v[140:141], v[224:225]
	global_store_dwordx4 v157, v[126:129], s[76:77] nt
	global_load_dwordx4 v[224:227], v157, s[74:75] offset:512 nt
	s_waitcnt vmcnt(6)
	v_pk_fma_f32 v[124:125], v[124:125], v[146:147], v[230:231]
	v_pk_fma_f32 v[122:123], v[122:123], v[144:145], v[228:229]
	global_store_dwordx4 v157, v[122:125], s[76:77] offset:64 nt
	global_load_dwordx4 v[228:231], v157, s[74:75] offset:576 nt
	s_waitcnt vmcnt(7)
	v_pk_fma_f32 v[120:121], v[120:121], v[150:151], v[234:235]
	v_pk_fma_f32 v[118:119], v[118:119], v[148:149], v[232:233]
	global_store_dwordx4 v157, v[118:121], s[76:77] offset:512 nt
	s_add_u32 s74, s74, 0x20000
	s_addc_u32 s75, s75, 0
	global_load_dwordx4 v[232:235], v157, s[74:75] nt
	s_waitcnt vmcnt(8)
	v_pk_fma_f32 v[116:117], v[116:117], v[170:171], v[238:239]
	v_pk_fma_f32 v[114:115], v[114:115], v[168:169], v[236:237]
	global_store_dwordx4 v157, v[114:117], s[76:77] offset:576 nt
	global_load_dwordx4 v[236:239], v157, s[74:75] offset:64 nt
	s_add_u32 s76, s76, 0x20000
	s_addc_u32 s77, s77, 0
	s_waitcnt vmcnt(9)
	v_pk_fma_f32 v[112:113], v[112:113], v[142:143], v[242:243]
	v_pk_fma_f32 v[110:111], v[110:111], v[140:141], v[240:241]
	global_store_dwordx4 v157, v[110:113], s[76:77] nt
	global_load_dwordx4 v[240:243], v157, s[74:75] offset:512 nt
	s_waitcnt vmcnt(10)
	v_pk_fma_f32 v[108:109], v[108:109], v[146:147], v[246:247]
	v_pk_fma_f32 v[106:107], v[106:107], v[144:145], v[244:245]
	global_store_dwordx4 v157, v[106:109], s[76:77] offset:64 nt
	global_load_dwordx4 v[244:247], v157, s[74:75] offset:576 nt
	s_waitcnt vmcnt(10)
	v_pk_fma_f32 v[104:105], v[104:105], v[150:151], v[226:227]
	v_pk_fma_f32 v[102:103], v[102:103], v[148:149], v[224:225]
	global_store_dwordx4 v157, v[102:105], s[76:77] offset:512 nt
	s_add_u32 s74, s74, 0x20000
	s_addc_u32 s75, s75, 0
	global_load_dwordx4 v[224:227], v157, s[74:75] nt
	s_waitcnt vmcnt(10)
	v_pk_fma_f32 v[100:101], v[100:101], v[170:171], v[230:231]
	v_pk_fma_f32 v[98:99], v[98:99], v[168:169], v[228:229]
	global_store_dwordx4 v157, v[98:101], s[76:77] offset:576 nt
	global_load_dwordx4 v[228:231], v157, s[74:75] offset:64 nt
	s_add_u32 s76, s76, 0x20000
	s_addc_u32 s77, s77, 0
	s_waitcnt vmcnt(10)
	v_pk_fma_f32 v[96:97], v[96:97], v[142:143], v[234:235]
	v_pk_fma_f32 v[94:95], v[94:95], v[140:141], v[232:233]
	global_store_dwordx4 v157, v[94:97], s[76:77] nt
	global_load_dwordx4 v[232:235], v157, s[74:75] offset:512 nt
	s_waitcnt vmcnt(10)
	v_pk_fma_f32 v[92:93], v[92:93], v[146:147], v[238:239]
	v_pk_fma_f32 v[90:91], v[90:91], v[144:145], v[236:237]
	global_store_dwordx4 v157, v[90:93], s[76:77] offset:64 nt
	global_load_dwordx4 v[236:239], v157, s[74:75] offset:576 nt
	s_waitcnt vmcnt(10)
	v_pk_fma_f32 v[88:89], v[88:89], v[150:151], v[242:243]
	v_pk_fma_f32 v[86:87], v[86:87], v[148:149], v[240:241]
	global_store_dwordx4 v157, v[86:89], s[76:77] offset:512 nt
	s_add_u32 s74, s74, 0xa0000
	s_addc_u32 s75, s75, 0
	global_load_dwordx4 v[240:243], v157, s[74:75] nt
	s_waitcnt vmcnt(10)
	v_pk_fma_f32 v[84:85], v[84:85], v[170:171], v[246:247]
	v_pk_fma_f32 v[82:83], v[82:83], v[168:169], v[244:245]
	global_store_dwordx4 v157, v[82:85], s[76:77] offset:576 nt
	global_load_dwordx4 v[244:247], v157, s[74:75] offset:64 nt
	s_add_u32 s76, s76, 0x20000
	s_addc_u32 s77, s77, 0
	s_waitcnt vmcnt(10)
	v_pk_fma_f32 v[80:81], v[80:81], v[142:143], v[226:227]
	v_pk_fma_f32 v[78:79], v[78:79], v[140:141], v[224:225]
	global_store_dwordx4 v157, v[78:81], s[76:77] nt
	global_load_dwordx4 v[224:227], v157, s[74:75] offset:512 nt
	s_waitcnt vmcnt(10)
	v_pk_fma_f32 v[76:77], v[76:77], v[146:147], v[230:231]
	v_pk_fma_f32 v[74:75], v[74:75], v[144:145], v[228:229]
	global_store_dwordx4 v157, v[74:77], s[76:77] offset:64 nt
	global_load_dwordx4 v[228:231], v157, s[74:75] offset:576 nt
	s_waitcnt vmcnt(10)
	v_pk_fma_f32 v[72:73], v[72:73], v[150:151], v[234:235]
	v_pk_fma_f32 v[70:71], v[70:71], v[148:149], v[232:233]
	global_store_dwordx4 v157, v[70:73], s[76:77] offset:512 nt
	s_add_u32 s74, s74, 0x20000
	s_addc_u32 s75, s75, 0
	global_load_dwordx4 v[232:235], v157, s[74:75] nt
	s_waitcnt vmcnt(10)
	v_pk_fma_f32 v[68:69], v[68:69], v[170:171], v[238:239]
	v_pk_fma_f32 v[66:67], v[66:67], v[168:169], v[236:237]
	global_store_dwordx4 v157, v[66:69], s[76:77] offset:576 nt
	global_load_dwordx4 v[236:239], v157, s[74:75] offset:64 nt
	s_add_u32 s76, s76, 0xa0000
	s_addc_u32 s77, s77, 0
	s_waitcnt vmcnt(10)
	v_pk_fma_f32 v[64:65], v[64:65], v[142:143], v[242:243]
	v_pk_fma_f32 v[62:63], v[62:63], v[140:141], v[240:241]
	global_store_dwordx4 v157, v[62:65], s[76:77] nt
	global_load_dwordx4 v[240:243], v157, s[74:75] offset:512 nt
	s_waitcnt vmcnt(10)
	v_pk_fma_f32 v[60:61], v[60:61], v[146:147], v[246:247]
	v_pk_fma_f32 v[58:59], v[58:59], v[144:145], v[244:245]
	global_store_dwordx4 v157, v[58:61], s[76:77] offset:64 nt
	global_load_dwordx4 v[244:247], v157, s[74:75] offset:576 nt
	s_waitcnt vmcnt(10)
	v_pk_fma_f32 v[56:57], v[56:57], v[150:151], v[226:227]
	v_pk_fma_f32 v[54:55], v[54:55], v[148:149], v[224:225]
	global_store_dwordx4 v157, v[54:57], s[76:77] offset:512 nt
	s_add_u32 s74, s74, 0x20000
	s_addc_u32 s75, s75, 0
	global_load_dwordx4 v[224:227], v157, s[74:75] nt
	s_waitcnt vmcnt(10)
	v_pk_fma_f32 v[52:53], v[52:53], v[170:171], v[230:231]
	v_pk_fma_f32 v[50:51], v[50:51], v[168:169], v[228:229]
	global_store_dwordx4 v157, v[50:53], s[76:77] offset:576 nt
	global_load_dwordx4 v[228:231], v157, s[74:75] offset:64 nt
	s_add_u32 s76, s76, 0x20000
	s_addc_u32 s77, s77, 0
	s_waitcnt vmcnt(10)
	v_pk_fma_f32 v[48:49], v[48:49], v[142:143], v[234:235]
	v_pk_fma_f32 v[46:47], v[46:47], v[140:141], v[232:233]
	global_store_dwordx4 v157, v[46:49], s[76:77] nt
	global_load_dwordx4 v[232:235], v157, s[74:75] offset:512 nt
	s_waitcnt vmcnt(10)
	v_pk_fma_f32 v[44:45], v[44:45], v[146:147], v[238:239]
	v_pk_fma_f32 v[42:43], v[42:43], v[144:145], v[236:237]
	global_store_dwordx4 v157, v[42:45], s[76:77] offset:64 nt
	global_load_dwordx4 v[236:239], v157, s[74:75] offset:576 nt
	s_waitcnt vmcnt(10)
	v_pk_fma_f32 v[40:41], v[40:41], v[150:151], v[242:243]
	v_pk_fma_f32 v[38:39], v[38:39], v[148:149], v[240:241]
	global_store_dwordx4 v157, v[38:41], s[76:77] offset:512 nt
	s_add_u32 s74, s74, 0x20000
	s_addc_u32 s75, s75, 0
	global_load_dwordx4 v[240:243], v157, s[74:75] nt
	s_waitcnt vmcnt(10)
	v_pk_fma_f32 v[36:37], v[36:37], v[170:171], v[246:247]
	v_pk_fma_f32 v[34:35], v[34:35], v[168:169], v[244:245]
	global_store_dwordx4 v157, v[34:37], s[76:77] offset:576 nt
	global_load_dwordx4 v[244:247], v157, s[74:75] offset:64 nt
	s_add_u32 s76, s76, 0x20000
	s_addc_u32 s77, s77, 0
	s_waitcnt vmcnt(10)
	v_pk_fma_f32 v[32:33], v[32:33], v[142:143], v[226:227]
	v_pk_fma_f32 v[30:31], v[30:31], v[140:141], v[224:225]
	global_store_dwordx4 v157, v[30:33], s[76:77] nt
	global_load_dwordx4 v[224:227], v157, s[74:75] offset:512 nt
	s_waitcnt vmcnt(10)
	v_pk_fma_f32 v[28:29], v[28:29], v[146:147], v[230:231]
	v_pk_fma_f32 v[26:27], v[26:27], v[144:145], v[228:229]
	global_store_dwordx4 v157, v[26:29], s[76:77] offset:64 nt
	global_load_dwordx4 v[228:231], v157, s[74:75] offset:576 nt
	s_waitcnt vmcnt(10)
	v_pk_fma_f32 v[24:25], v[24:25], v[150:151], v[234:235]
	v_pk_fma_f32 v[22:23], v[22:23], v[148:149], v[232:233]
	global_store_dwordx4 v157, v[22:25], s[76:77] offset:512 nt
	s_waitcnt vmcnt(9)
	v_pk_fma_f32 v[20:21], v[20:21], v[170:171], v[238:239]
	v_pk_fma_f32 v[18:19], v[18:19], v[168:169], v[236:237]
	global_store_dwordx4 v157, v[18:21], s[76:77] offset:576 nt
	s_add_u32 s76, s76, 0x20000
	s_addc_u32 s77, s77, 0
	s_waitcnt vmcnt(8)
	v_pk_fma_f32 v[16:17], v[16:17], v[142:143], v[242:243]
	v_pk_fma_f32 v[14:15], v[14:15], v[140:141], v[240:241]
	global_store_dwordx4 v157, v[14:17], s[76:77] nt
	s_waitcnt vmcnt(7)
	v_pk_fma_f32 v[12:13], v[12:13], v[146:147], v[246:247]
	v_pk_fma_f32 v[10:11], v[10:11], v[144:145], v[244:245]
	global_store_dwordx4 v157, v[10:13], s[76:77] offset:64 nt
	s_waitcnt vmcnt(6)
	v_pk_fma_f32 v[8:9], v[8:9], v[150:151], v[226:227]
	v_pk_fma_f32 v[6:7], v[6:7], v[148:149], v[224:225]
	global_store_dwordx4 v157, v[6:9], s[76:77] offset:512 nt
	s_waitcnt vmcnt(5)
	v_pk_fma_f32 v[4:5], v[4:5], v[170:171], v[230:231]
	v_pk_fma_f32 v[2:3], v[2:3], v[168:169], v[228:229]
	global_store_dwordx4 v157, v[2:5], s[76:77] offset:576 nt
	s_branch .LBB0_24

.LBB0_234:
	s_add_u32 s39, s46, 0xfff80080
	s_addc_u32 s48, s47, -1
	s_add_i32 s62, 0, 0x10000
	v_add_u32_e32 v156, s62, v141
	ds_read_b128 v[144:147], v156
	ds_read_b128 v[148:151], v156 offset:1024
	ds_read_b128 v[152:155], v156 offset:2048
	ds_read_b128 v[168:171], v156 offset:3072
	s_cmp_eq_u32 s13, 28
	s_cselect_b32 s51, s43, s48
	s_cselect_b32 s50, s42, s39
	s_cselect_b32 s49, s45, s12
	s_cselect_b32 s48, s44, s1
	ds_read_b128 v[172:175], v143
	ds_read_b128 v[176:179], v143 offset:1024
	ds_read_b128 v[180:183], v143 offset:2048
	ds_read_b128 v[184:187], v143 offset:3072
	ds_read_b128 v[188:191], v143 offset:4096
	ds_read_b128 v[192:195], v143 offset:5120
	ds_read_b128 v[196:199], v143 offset:6144
	ds_read_b128 v[224:227], v143 offset:7168
	s_add_i32 m0, s53, 0xc000
	s_nop 0
	global_load_lds_dwordx4 v136, s[46:47]
	s_add_i32 m0, s53, 0xe000
	s_nop 0
	global_load_lds_dwordx4 v138, s[46:47]
	s_add_i32 s39, 0, 0x14000
	v_add_u32_e32 v156, s39, v141
	s_add_i32 s62, s62, s52
	ds_read_b128 v[228:231], v156
	ds_read_b128 v[232:235], v156 offset:1024
	ds_read_b128 v[236:239], v156 offset:2048
	ds_read_b128 v[240:243], v156 offset:3072
	s_waitcnt lgkmcnt(0)
	s_barrier
	v_mfma_f32_16x16x32_bf16 v[126:129], v[144:147], v[172:175], v[126:129]
	v_mfma_f32_16x16x32_bf16 v[122:125], v[152:155], v[172:175], v[122:125]
	v_mfma_f32_16x16x32_bf16 v[118:121], v[144:147], v[180:183], v[118:121]
	v_mfma_f32_16x16x32_bf16 v[114:117], v[152:155], v[180:183], v[114:117]
	v_mfma_f32_16x16x32_bf16 v[102:105], v[144:147], v[188:191], v[102:105]
	v_mfma_f32_16x16x32_bf16 v[98:101], v[152:155], v[188:191], v[98:101]
	v_mfma_f32_16x16x32_bf16 v[86:89], v[144:147], v[196:199], v[86:89]
	v_mfma_f32_16x16x32_bf16 v[82:85], v[152:155], v[196:199], v[82:85]
	v_mfma_f32_16x16x32_bf16 v[126:129], v[148:151], v[176:179], v[126:129]
	v_mfma_f32_16x16x32_bf16 v[122:125], v[168:171], v[176:179], v[122:125]
	v_mfma_f32_16x16x32_bf16 v[118:121], v[148:151], v[184:187], v[118:121]
	v_mfma_f32_16x16x32_bf16 v[114:117], v[168:171], v[184:187], v[114:117]
	v_mfma_f32_16x16x32_bf16 v[102:105], v[148:151], v[192:195], v[102:105]
	v_mfma_f32_16x16x32_bf16 v[98:101], v[168:171], v[192:195], v[98:101]
	v_mfma_f32_16x16x32_bf16 v[86:89], v[148:151], v[224:227], v[86:89]
	v_mfma_f32_16x16x32_bf16 v[82:85], v[168:171], v[224:227], v[82:85]
	v_mfma_f32_16x16x32_bf16 v[110:113], v[228:231], v[172:175], v[110:113]
	v_mfma_f32_16x16x32_bf16 v[106:109], v[236:239], v[172:175], v[106:109]
	v_mfma_f32_16x16x32_bf16 v[94:97], v[228:231], v[180:183], v[94:97]
	v_mfma_f32_16x16x32_bf16 v[90:93], v[236:239], v[180:183], v[90:93]
	v_mfma_f32_16x16x32_bf16 v[78:81], v[228:231], v[188:191], v[78:81]
	v_mfma_f32_16x16x32_bf16 v[74:77], v[236:239], v[188:191], v[74:77]
	v_mfma_f32_16x16x32_bf16 v[70:73], v[228:231], v[196:199], v[70:73]
	v_mfma_f32_16x16x32_bf16 v[66:69], v[236:239], v[196:199], v[66:69]
	v_mfma_f32_16x16x32_bf16 v[110:113], v[232:235], v[176:179], v[110:113]
	v_mfma_f32_16x16x32_bf16 v[106:109], v[240:243], v[176:179], v[106:109]
	v_mfma_f32_16x16x32_bf16 v[94:97], v[232:235], v[184:187], v[94:97]
	v_mfma_f32_16x16x32_bf16 v[90:93], v[240:243], v[184:187], v[90:93]
	v_mfma_f32_16x16x32_bf16 v[78:81], v[232:235], v[192:195], v[78:81]
	v_mfma_f32_16x16x32_bf16 v[74:77], v[240:243], v[192:195], v[74:77]
	v_mfma_f32_16x16x32_bf16 v[70:73], v[232:235], v[224:227], v[70:73]
	v_mfma_f32_16x16x32_bf16 v[66:69], v[240:243], v[224:227], v[66:69]
	s_barrier
	s_mov_b32 m0, s53
	s_add_u32 s78, s50, s94
	s_addc_u32 s79, s51, s95
	ds_read_b128 v[172:175], v143 offset:16384
	ds_read_b128 v[176:179], v143 offset:17408
	ds_read_b128 v[180:183], v143 offset:18432
	ds_read_b128 v[184:187], v143 offset:19456
	ds_read_b128 v[188:191], v143 offset:20480
	ds_read_b128 v[192:195], v143 offset:21504
	ds_read_b128 v[196:199], v143 offset:22528
	ds_read_b128 v[224:227], v143 offset:23552
	global_load_lds_dwordx4 v134, s[50:51]
	s_mov_b32 m0, s54
	s_nop 0
	global_load_lds_dwordx4 v132, s[50:51]
	s_add_u32 s76, s48, s94
	s_addc_u32 s77, s49, s95
	s_mov_b32 m0, s62
	s_nop 0
	global_load_lds_dwordx4 v0, s[48:49]
	s_add_i32 m0, s62, 0x2000
	s_nop 0
	global_load_lds_dwordx4 v130, s[48:49]
	s_add_u32 s62, s48, 0x80000
	s_addc_u32 s63, s49, 0
	s_add_i32 s39, s39, s52
	s_mov_b32 m0, s39
	s_nop 0
	global_load_lds_dwordx4 v0, s[62:63]
	s_add_i32 m0, s39, 0x2000
	s_nop 0
	global_load_lds_dwordx4 v130, s[62:63]
	s_waitcnt vmcnt(6) lgkmcnt(0)
	s_barrier
	v_mfma_f32_16x16x32_bf16 v[62:65], v[144:147], v[172:175], v[62:65]
	v_mfma_f32_16x16x32_bf16 v[58:61], v[152:155], v[172:175], v[58:61]
	v_mfma_f32_16x16x32_bf16 v[54:57], v[144:147], v[180:183], v[54:57]
	v_mfma_f32_16x16x32_bf16 v[50:53], v[152:155], v[180:183], v[50:53]
	v_mfma_f32_16x16x32_bf16 v[38:41], v[144:147], v[188:191], v[38:41]
	v_mfma_f32_16x16x32_bf16 v[34:37], v[152:155], v[188:191], v[34:37]
	v_mfma_f32_16x16x32_bf16 v[22:25], v[144:147], v[196:199], v[22:25]
	v_mfma_f32_16x16x32_bf16 v[18:21], v[152:155], v[196:199], v[18:21]
	v_mfma_f32_16x16x32_bf16 v[62:65], v[148:151], v[176:179], v[62:65]
	v_mfma_f32_16x16x32_bf16 v[58:61], v[168:171], v[176:179], v[58:61]
	v_mfma_f32_16x16x32_bf16 v[54:57], v[148:151], v[184:187], v[54:57]
	v_mfma_f32_16x16x32_bf16 v[50:53], v[168:171], v[184:187], v[50:53]
	v_mfma_f32_16x16x32_bf16 v[38:41], v[148:151], v[192:195], v[38:41]
	v_mfma_f32_16x16x32_bf16 v[34:37], v[168:171], v[192:195], v[34:37]
	v_mfma_f32_16x16x32_bf16 v[22:25], v[148:151], v[224:227], v[22:25]
	v_mfma_f32_16x16x32_bf16 v[18:21], v[168:171], v[224:227], v[18:21]
	v_mfma_f32_16x16x32_bf16 v[46:49], v[228:231], v[172:175], v[46:49]
	v_mfma_f32_16x16x32_bf16 v[42:45], v[236:239], v[172:175], v[42:45]
	v_mfma_f32_16x16x32_bf16 v[30:33], v[228:231], v[180:183], v[30:33]
	v_mfma_f32_16x16x32_bf16 v[26:29], v[236:239], v[180:183], v[26:29]
	v_mfma_f32_16x16x32_bf16 v[14:17], v[228:231], v[188:191], v[14:17]
	v_mfma_f32_16x16x32_bf16 v[10:13], v[236:239], v[188:191], v[10:13]
	v_mfma_f32_16x16x32_bf16 v[6:9], v[228:231], v[196:199], v[6:9]
	v_mfma_f32_16x16x32_bf16 v[2:5], v[236:239], v[196:199], v[2:5]
	v_mfma_f32_16x16x32_bf16 v[46:49], v[232:235], v[176:179], v[46:49]
	v_mfma_f32_16x16x32_bf16 v[42:45], v[240:243], v[176:179], v[42:45]
	v_mfma_f32_16x16x32_bf16 v[30:33], v[232:235], v[184:187], v[30:33]
	v_mfma_f32_16x16x32_bf16 v[26:29], v[240:243], v[184:187], v[26:29]
	v_mfma_f32_16x16x32_bf16 v[14:17], v[232:235], v[192:195], v[14:17]
	v_mfma_f32_16x16x32_bf16 v[10:13], v[240:243], v[192:195], v[10:13]
	v_mfma_f32_16x16x32_bf16 v[6:9], v[232:235], v[224:227], v[6:9]
	v_mfma_f32_16x16x32_bf16 v[2:5], v[240:243], v[224:227], v[2:5]
	s_barrier
	s_add_i32 s39, 0, 0x18000
	v_add_u32_e32 v161, s39, v141
	ds_read_b128 v[144:147], v161
	ds_read_b128 v[148:151], v161 offset:1024
	ds_read_b128 v[152:155], v161 offset:2048
	ds_read_b128 v[168:171], v161 offset:3072
	s_add_u32 s50, s50, 0x80000
	s_addc_u32 s51, s51, 0
	ds_read_b128 v[172:175], v143 offset:32768
	ds_read_b128 v[176:179], v143 offset:33792
	ds_read_b128 v[180:183], v143 offset:34816
	ds_read_b128 v[184:187], v143 offset:35840
	ds_read_b128 v[188:191], v143 offset:36864
	ds_read_b128 v[192:195], v143 offset:37888
	ds_read_b128 v[196:199], v143 offset:38912
	ds_read_b128 v[224:227], v143 offset:39936
	s_mov_b32 m0, s55
	s_nop 0
	global_load_lds_dwordx4 v134, s[50:51]
	s_mov_b32 m0, s56
	s_nop 0
	global_load_lds_dwordx4 v132, s[50:51]
	s_add_i32 s50, 0, 0x1c000
	s_add_i32 s39, s39, s52
	v_add_u32_e32 v161, s50, v141
	ds_read_b128 v[228:231], v161
	ds_read_b128 v[232:235], v161 offset:1024
	ds_read_b128 v[236:239], v161 offset:2048
	ds_read_b128 v[240:243], v161 offset:3072
	s_waitcnt lgkmcnt(0)
	s_barrier
	v_mfma_f32_16x16x32_bf16 v[126:129], v[144:147], v[172:175], v[126:129]
	v_mfma_f32_16x16x32_bf16 v[122:125], v[152:155], v[172:175], v[122:125]
	v_mfma_f32_16x16x32_bf16 v[118:121], v[144:147], v[180:183], v[118:121]
	v_mfma_f32_16x16x32_bf16 v[114:117], v[152:155], v[180:183], v[114:117]
	v_mfma_f32_16x16x32_bf16 v[102:105], v[144:147], v[188:191], v[102:105]
	v_mfma_f32_16x16x32_bf16 v[98:101], v[152:155], v[188:191], v[98:101]
	v_mfma_f32_16x16x32_bf16 v[86:89], v[144:147], v[196:199], v[86:89]
	v_mfma_f32_16x16x32_bf16 v[82:85], v[152:155], v[196:199], v[82:85]
	v_mfma_f32_16x16x32_bf16 v[126:129], v[148:151], v[176:179], v[126:129]
	v_mfma_f32_16x16x32_bf16 v[122:125], v[168:171], v[176:179], v[122:125]
	v_mfma_f32_16x16x32_bf16 v[118:121], v[148:151], v[184:187], v[118:121]
	v_mfma_f32_16x16x32_bf16 v[114:117], v[168:171], v[184:187], v[114:117]
	v_mfma_f32_16x16x32_bf16 v[102:105], v[148:151], v[192:195], v[102:105]
	v_mfma_f32_16x16x32_bf16 v[98:101], v[168:171], v[192:195], v[98:101]
	v_mfma_f32_16x16x32_bf16 v[86:89], v[148:151], v[224:227], v[86:89]
	v_mfma_f32_16x16x32_bf16 v[82:85], v[168:171], v[224:227], v[82:85]
	v_mfma_f32_16x16x32_bf16 v[110:113], v[228:231], v[172:175], v[110:113]
	v_mfma_f32_16x16x32_bf16 v[106:109], v[236:239], v[172:175], v[106:109]
	v_mfma_f32_16x16x32_bf16 v[94:97], v[228:231], v[180:183], v[94:97]
	v_mfma_f32_16x16x32_bf16 v[90:93], v[236:239], v[180:183], v[90:93]
	v_mfma_f32_16x16x32_bf16 v[78:81], v[228:231], v[188:191], v[78:81]
	v_mfma_f32_16x16x32_bf16 v[74:77], v[236:239], v[188:191], v[74:77]
	v_mfma_f32_16x16x32_bf16 v[70:73], v[228:231], v[196:199], v[70:73]
	v_mfma_f32_16x16x32_bf16 v[66:69], v[236:239], v[196:199], v[66:69]
	v_mfma_f32_16x16x32_bf16 v[110:113], v[232:235], v[176:179], v[110:113]
	v_mfma_f32_16x16x32_bf16 v[106:109], v[240:243], v[176:179], v[106:109]
	v_mfma_f32_16x16x32_bf16 v[94:97], v[232:235], v[184:187], v[94:97]
	v_mfma_f32_16x16x32_bf16 v[90:93], v[240:243], v[184:187], v[90:93]
	v_mfma_f32_16x16x32_bf16 v[78:81], v[232:235], v[192:195], v[78:81]
	v_mfma_f32_16x16x32_bf16 v[74:77], v[240:243], v[192:195], v[74:77]
	v_mfma_f32_16x16x32_bf16 v[70:73], v[232:235], v[224:227], v[70:73]
	v_mfma_f32_16x16x32_bf16 v[66:69], v[240:243], v[224:227], v[66:69]
	s_barrier
	s_mov_b32 m0, s57
	ds_read_b128 v[172:175], v143 offset:49152
	ds_read_b128 v[176:179], v143 offset:50176
	ds_read_b128 v[180:183], v143 offset:51200
	ds_read_b128 v[184:187], v143 offset:52224
	ds_read_b128 v[188:191], v143 offset:53248
	ds_read_b128 v[192:195], v143 offset:54272
	ds_read_b128 v[196:199], v143 offset:55296
	ds_read_b128 v[224:227], v143 offset:56320
	global_load_lds_dwordx4 v134, s[78:79]
	s_mov_b32 m0, s58
	s_nop 0
	global_load_lds_dwordx4 v132, s[78:79]
	s_mov_b32 m0, s39
	s_nop 0
	global_load_lds_dwordx4 v0, s[76:77]
	s_add_i32 m0, s39, 0x2000
	s_nop 0
	global_load_lds_dwordx4 v130, s[76:77]
	s_add_u32 s48, s48, 0x80080
	s_addc_u32 s49, s49, 0
	s_add_i32 s39, s50, s52
	s_mov_b32 m0, s39
	s_nop 0
	global_load_lds_dwordx4 v0, s[48:49]
	s_add_i32 m0, s39, 0x2000
	s_nop 0
	global_load_lds_dwordx4 v130, s[48:49]
	s_waitcnt vmcnt(6) lgkmcnt(0)
	s_barrier
	v_mfma_f32_16x16x32_bf16 v[62:65], v[144:147], v[172:175], v[62:65]
	v_mfma_f32_16x16x32_bf16 v[58:61], v[152:155], v[172:175], v[58:61]
	v_mfma_f32_16x16x32_bf16 v[54:57], v[144:147], v[180:183], v[54:57]
	v_mfma_f32_16x16x32_bf16 v[50:53], v[152:155], v[180:183], v[50:53]
	v_mfma_f32_16x16x32_bf16 v[38:41], v[144:147], v[188:191], v[38:41]
	v_mfma_f32_16x16x32_bf16 v[34:37], v[152:155], v[188:191], v[34:37]
	v_mfma_f32_16x16x32_bf16 v[22:25], v[144:147], v[196:199], v[22:25]
	v_mfma_f32_16x16x32_bf16 v[18:21], v[152:155], v[196:199], v[18:21]
	v_mfma_f32_16x16x32_bf16 v[62:65], v[148:151], v[176:179], v[62:65]
	v_mfma_f32_16x16x32_bf16 v[58:61], v[168:171], v[176:179], v[58:61]
	v_mfma_f32_16x16x32_bf16 v[54:57], v[148:151], v[184:187], v[54:57]
	v_mfma_f32_16x16x32_bf16 v[50:53], v[168:171], v[184:187], v[50:53]
	v_mfma_f32_16x16x32_bf16 v[38:41], v[148:151], v[192:195], v[38:41]
	v_mfma_f32_16x16x32_bf16 v[34:37], v[168:171], v[192:195], v[34:37]
	v_mfma_f32_16x16x32_bf16 v[22:25], v[148:151], v[224:227], v[22:25]
	v_mfma_f32_16x16x32_bf16 v[18:21], v[168:171], v[224:227], v[18:21]
	v_mfma_f32_16x16x32_bf16 v[46:49], v[228:231], v[172:175], v[46:49]
	v_mfma_f32_16x16x32_bf16 v[42:45], v[236:239], v[172:175], v[42:45]
	v_mfma_f32_16x16x32_bf16 v[30:33], v[228:231], v[180:183], v[30:33]
	v_mfma_f32_16x16x32_bf16 v[26:29], v[236:239], v[180:183], v[26:29]
	v_mfma_f32_16x16x32_bf16 v[14:17], v[228:231], v[188:191], v[14:17]
	v_mfma_f32_16x16x32_bf16 v[10:13], v[236:239], v[188:191], v[10:13]
	v_mfma_f32_16x16x32_bf16 v[6:9], v[228:231], v[196:199], v[6:9]
	v_mfma_f32_16x16x32_bf16 v[2:5], v[236:239], v[196:199], v[2:5]
	v_mfma_f32_16x16x32_bf16 v[46:49], v[232:235], v[176:179], v[46:49]
	v_mfma_f32_16x16x32_bf16 v[42:45], v[240:243], v[176:179], v[42:45]
	v_mfma_f32_16x16x32_bf16 v[30:33], v[232:235], v[184:187], v[30:33]
	v_mfma_f32_16x16x32_bf16 v[26:29], v[240:243], v[184:187], v[26:29]
	v_mfma_f32_16x16x32_bf16 v[14:17], v[232:235], v[192:195], v[14:17]
	v_mfma_f32_16x16x32_bf16 v[10:13], v[240:243], v[192:195], v[10:13]
	v_mfma_f32_16x16x32_bf16 v[6:9], v[232:235], v[224:227], v[6:9]
	v_mfma_f32_16x16x32_bf16 v[2:5], v[240:243], v[224:227], v[2:5]
	s_barrier
	s_add_i32 s13, s13, 2
	s_add_u32 s46, s46, 0x100
	s_addc_u32 s47, s47, 0
	s_add_u32 s1, s1, 0x100
	s_addc_u32 s12, s12, 0
	s_cmp_gt_u32 s13, 29
	s_cbranch_scc0 .LBB0_234
	v_readlane_b32 s6, v255, 23
	v_lshl_add_u32 v150, s61, 8, v140
	v_lshl_or_b32 v144, s60, 8, v142
	v_readlane_b32 s7, v255, 24
	v_ashrrev_i32_e32 v145, 31, v144
	s_movk_i32 s1, 0x5800
	v_mov_b64_e32 v[146:147], s[6:7]
	v_cvt_pk_bf16_f32 v70, v70, v71
	v_cvt_pk_bf16_f32 v71, v72, v73
	v_cvt_pk_bf16_f32 v72, v66, v67
	v_add_u32_e32 v66, 0x80, v150
	v_mad_i64_i32 v[148:149], s[12:13], v150, s1, v[146:147]
	v_lshlrev_b64 v[144:145], 1, v[144:145]
	v_cvt_pk_bf16_f32 v110, v110, v111
	v_cvt_pk_bf16_f32 v111, v112, v113
	v_cvt_pk_bf16_f32 v112, v106, v107
	v_or_b32_e32 v106, 16, v150
	v_mad_i64_i32 v[66:67], s[12:13], v66, s1, v[146:147]
	v_cvt_pk_bf16_f32 v46, v46, v47
	v_cvt_pk_bf16_f32 v47, v48, v49
	v_cvt_pk_bf16_f32 v48, v42, v43
	v_add_u32_e32 v42, 0x90, v150
	v_lshl_add_u64 v[148:149], v[148:149], 0, v[144:145]
	v_cvt_pk_bf16_f32 v113, v108, v109
	v_mad_i64_i32 v[106:107], s[12:13], v106, s1, v[146:147]
	v_cvt_pk_bf16_f32 v94, v94, v95
	v_cvt_pk_bf16_f32 v95, v96, v97
	v_cvt_pk_bf16_f32 v96, v90, v91
	v_or_b32_e32 v90, 32, v150
	v_lshl_add_u64 v[66:67], v[66:67], 0, v[144:145]
	v_cvt_pk_bf16_f32 v49, v44, v45
	v_mad_i64_i32 v[42:43], s[12:13], v42, s1, v[146:147]
	v_cvt_pk_bf16_f32 v30, v30, v31
	v_cvt_pk_bf16_f32 v31, v32, v33
	v_cvt_pk_bf16_f32 v32, v26, v27
	v_add_u32_e32 v26, 0xa0, v150
	global_store_dwordx4 v[148:149], v[110:113], off offset:256
	v_cvt_pk_bf16_f32 v97, v92, v93
	v_mad_i64_i32 v[90:91], s[12:13], v90, s1, v[146:147]
	v_lshl_add_u64 v[110:111], v[106:107], 0, v[144:145]
	v_cvt_pk_bf16_f32 v78, v78, v79
	v_cvt_pk_bf16_f32 v79, v80, v81
	v_cvt_pk_bf16_f32 v80, v74, v75
	v_or_b32_e32 v74, 48, v150
	global_store_dwordx4 v[66:67], v[46:49], off offset:256
	v_cvt_pk_bf16_f32 v33, v28, v29
	v_mad_i64_i32 v[26:27], s[12:13], v26, s1, v[146:147]
	v_lshl_add_u64 v[46:47], v[42:43], 0, v[144:145]
	v_cvt_pk_bf16_f32 v14, v14, v15
	v_cvt_pk_bf16_f32 v15, v16, v17
	v_cvt_pk_bf16_f32 v16, v10, v11
	v_add_u32_e32 v10, 0xb0, v150
	global_store_dwordx4 v[110:111], v[94:97], off offset:256
	v_cvt_pk_bf16_f32 v81, v76, v77
	v_mad_i64_i32 v[74:75], s[12:13], v74, s1, v[146:147]
	v_lshl_add_u64 v[94:95], v[90:91], 0, v[144:145]
	global_store_dwordx4 v[46:47], v[30:33], off offset:256
	v_cvt_pk_bf16_f32 v17, v12, v13
	v_mad_i64_i32 v[10:11], s[12:13], v10, s1, v[146:147]
	v_lshl_add_u64 v[30:31], v[26:27], 0, v[144:145]
	v_cvt_pk_bf16_f32 v126, v126, v127
	v_cvt_pk_bf16_f32 v127, v128, v129
	v_cvt_pk_bf16_f32 v128, v122, v123
	v_cvt_pk_bf16_f32 v129, v124, v125
	v_cvt_pk_bf16_f32 v106, v118, v119
	v_cvt_pk_bf16_f32 v107, v120, v121
	v_cvt_pk_bf16_f32 v108, v114, v115
	v_cvt_pk_bf16_f32 v109, v116, v117
	v_cvt_pk_bf16_f32 v90, v102, v103
	v_cvt_pk_bf16_f32 v91, v104, v105
	v_cvt_pk_bf16_f32 v92, v98, v99
	v_cvt_pk_bf16_f32 v93, v100, v101
	global_store_dwordx4 v[94:95], v[78:81], off offset:256
	v_cvt_pk_bf16_f32 v76, v82, v83
	v_cvt_pk_bf16_f32 v77, v84, v85
	v_lshl_add_u64 v[78:79], v[74:75], 0, v[144:145]
	v_cvt_pk_bf16_f32 v74, v86, v87
	v_cvt_pk_bf16_f32 v75, v88, v89
	v_cvt_pk_bf16_f32 v73, v68, v69
	v_cvt_pk_bf16_f32 v62, v62, v63
	v_cvt_pk_bf16_f32 v63, v64, v65
	v_cvt_pk_bf16_f32 v64, v58, v59
	v_cvt_pk_bf16_f32 v65, v60, v61
	v_cvt_pk_bf16_f32 v42, v54, v55
	v_cvt_pk_bf16_f32 v43, v56, v57
	v_cvt_pk_bf16_f32 v44, v50, v51
	v_cvt_pk_bf16_f32 v45, v52, v53
	v_cvt_pk_bf16_f32 v26, v38, v39
	v_cvt_pk_bf16_f32 v27, v40, v41
	v_cvt_pk_bf16_f32 v28, v34, v35
	v_cvt_pk_bf16_f32 v29, v36, v37
	global_store_dwordx4 v[30:31], v[14:17], off offset:256
	v_cvt_pk_bf16_f32 v12, v18, v19
	v_cvt_pk_bf16_f32 v13, v20, v21
	v_lshl_add_u64 v[14:15], v[10:11], 0, v[144:145]
	v_cvt_pk_bf16_f32 v10, v22, v23
	v_cvt_pk_bf16_f32 v11, v24, v25
	v_cvt_pk_bf16_f32 v6, v6, v7
	v_cvt_pk_bf16_f32 v7, v8, v9
	v_cvt_pk_bf16_f32 v8, v2, v3
	v_cvt_pk_bf16_f32 v9, v4, v5
	s_and_b64 vcc, exec, s[40:41]
	s_mov_b32 s60, s0
	s_mov_b32 s61, s38
	s_mov_b64 s[48:49], s[44:45]
	s_mov_b64 s[46:47], s[42:43]
	global_store_dwordx4 v[148:149], v[126:129], off
	global_store_dwordx4 v[110:111], v[106:109], off
	global_store_dwordx4 v[94:95], v[90:93], off
	global_store_dwordx4 v[78:79], v[74:77], off
	global_store_dwordx4 v[78:79], v[70:73], off offset:256
	global_store_dwordx4 v[66:67], v[62:65], off
	global_store_dwordx4 v[46:47], v[42:45], off
	global_store_dwordx4 v[30:31], v[26:29], off
	global_store_dwordx4 v[14:15], v[10:13], off
	global_store_dwordx4 v[14:15], v[6:9], off offset:256
	s_cbranch_vccz .LBB0_227
	s_waitcnt vmcnt(0)
	v_readlane_b32 s60, v255, 21
	s_cmpk_gt_u32 s36, 0xff
	s_mov_b32 s18, s60
	v_readlane_b32 s61, v255, 22
	s_cbranch_scc1 .LBB0_238
	s_barrier

.LBB0_282:
	s_add_i32 s67, s50, 2
	s_add_u32 s51, s0, 0xfff80080
	s_addc_u32 s52, s1, -1
	s_add_i32 s68, 0, 0x10000
	v_add_u32_e32 v148, s68, v153
	ds_read_b128 v[136:139], v148
	ds_read_b128 v[140:143], v148 offset:1024
	ds_read_b128 v[144:147], v148 offset:2048
	ds_read_b128 v[148:151], v148 offset:3072
	s_cmp_eq_u32 s12, s50
	s_cselect_b32 s50, s48, s13
	s_cselect_b32 s53, s47, s52
	s_cselect_b32 s52, s46, s51
	s_cselect_b32 s51, s49, s66
	ds_read_b128 v[168:171], v155
	ds_read_b128 v[172:175], v155 offset:1024
	ds_read_b128 v[176:179], v155 offset:2048
	ds_read_b128 v[180:183], v155 offset:3072
	ds_read_b128 v[184:187], v155 offset:4096
	ds_read_b128 v[188:191], v155 offset:5120
	ds_read_b128 v[192:195], v155 offset:6144
	ds_read_b128 v[196:199], v155 offset:7168
	s_add_i32 m0, s55, 0xc000
	s_nop 0
	global_load_lds_dwordx4 v132, s[0:1]
	s_add_i32 m0, s55, 0xe000
	s_nop 0
	global_load_lds_dwordx4 v134, s[0:1]
	s_add_i32 s70, 0, 0x14000
	v_add_u32_e32 v156, s70, v153
	s_add_i32 s68, s68, s54
	ds_read_b128 v[224:227], v156
	ds_read_b128 v[228:231], v156 offset:1024
	ds_read_b128 v[232:235], v156 offset:2048
	ds_read_b128 v[236:239], v156 offset:3072
	s_waitcnt lgkmcnt(0)
	s_barrier
	v_mfma_f32_16x16x32_bf16 v[126:129], v[136:139], v[168:171], v[126:129]
	v_mfma_f32_16x16x32_bf16 v[122:125], v[144:147], v[168:171], v[122:125]
	v_mfma_f32_16x16x32_bf16 v[110:113], v[136:139], v[176:179], v[110:113]
	v_mfma_f32_16x16x32_bf16 v[106:109], v[144:147], v[176:179], v[106:109]
	v_mfma_f32_16x16x32_bf16 v[94:97], v[136:139], v[184:187], v[94:97]
	v_mfma_f32_16x16x32_bf16 v[90:93], v[144:147], v[184:187], v[90:93]
	v_mfma_f32_16x16x32_bf16 v[78:81], v[136:139], v[192:195], v[78:81]
	v_mfma_f32_16x16x32_bf16 v[74:77], v[144:147], v[192:195], v[74:77]
	v_mfma_f32_16x16x32_bf16 v[126:129], v[140:143], v[172:175], v[126:129]
	v_mfma_f32_16x16x32_bf16 v[122:125], v[148:151], v[172:175], v[122:125]
	v_mfma_f32_16x16x32_bf16 v[110:113], v[140:143], v[180:183], v[110:113]
	v_mfma_f32_16x16x32_bf16 v[106:109], v[148:151], v[180:183], v[106:109]
	v_mfma_f32_16x16x32_bf16 v[94:97], v[140:143], v[188:191], v[94:97]
	v_mfma_f32_16x16x32_bf16 v[90:93], v[148:151], v[188:191], v[90:93]
	v_mfma_f32_16x16x32_bf16 v[78:81], v[140:143], v[196:199], v[78:81]
	v_mfma_f32_16x16x32_bf16 v[74:77], v[148:151], v[196:199], v[74:77]
	v_mfma_f32_16x16x32_bf16 v[118:121], v[224:227], v[168:171], v[118:121]
	v_mfma_f32_16x16x32_bf16 v[114:117], v[232:235], v[168:171], v[114:117]
	v_mfma_f32_16x16x32_bf16 v[102:105], v[224:227], v[176:179], v[102:105]
	v_mfma_f32_16x16x32_bf16 v[98:101], v[232:235], v[176:179], v[98:101]
	v_mfma_f32_16x16x32_bf16 v[86:89], v[224:227], v[184:187], v[86:89]
	v_mfma_f32_16x16x32_bf16 v[82:85], v[232:235], v[184:187], v[82:85]
	v_mfma_f32_16x16x32_bf16 v[70:73], v[224:227], v[192:195], v[70:73]
	v_mfma_f32_16x16x32_bf16 v[66:69], v[232:235], v[192:195], v[66:69]
	v_mfma_f32_16x16x32_bf16 v[118:121], v[228:231], v[172:175], v[118:121]
	v_mfma_f32_16x16x32_bf16 v[114:117], v[236:239], v[172:175], v[114:117]
	v_mfma_f32_16x16x32_bf16 v[102:105], v[228:231], v[180:183], v[102:105]
	v_mfma_f32_16x16x32_bf16 v[98:101], v[236:239], v[180:183], v[98:101]
	v_mfma_f32_16x16x32_bf16 v[86:89], v[228:231], v[188:191], v[86:89]
	v_mfma_f32_16x16x32_bf16 v[82:85], v[236:239], v[188:191], v[82:85]
	v_mfma_f32_16x16x32_bf16 v[70:73], v[228:231], v[196:199], v[70:73]
	v_mfma_f32_16x16x32_bf16 v[66:69], v[236:239], v[196:199], v[66:69]
	s_barrier
	s_mov_b32 m0, s55
	s_add_u32 s78, s52, s94
	s_addc_u32 s79, s53, s95
	ds_read_b128 v[168:171], v155 offset:16384
	ds_read_b128 v[172:175], v155 offset:17408
	ds_read_b128 v[176:179], v155 offset:18432
	ds_read_b128 v[180:183], v155 offset:19456
	ds_read_b128 v[184:187], v155 offset:20480
	ds_read_b128 v[188:191], v155 offset:21504
	ds_read_b128 v[192:195], v155 offset:22528
	ds_read_b128 v[196:199], v155 offset:23552
	global_load_lds_dwordx4 v0, s[52:53]
	s_mov_b32 m0, s56
	s_nop 0
	global_load_lds_dwordx4 v130, s[52:53]
	s_add_u32 s76, s50, s94
	s_addc_u32 s77, s51, s95
	s_mov_b32 m0, s68
	s_nop 0
	global_load_lds_dwordx4 v0, s[50:51]
	s_add_i32 m0, s68, 0x2000
	s_nop 0
	global_load_lds_dwordx4 v130, s[50:51]
	s_add_u32 s68, s50, 0x80000
	s_addc_u32 s69, s51, 0
	s_add_i32 s70, s70, s54
	s_mov_b32 m0, s70
	s_nop 0
	global_load_lds_dwordx4 v0, s[68:69]
	s_add_i32 m0, s70, 0x2000
	s_nop 0
	global_load_lds_dwordx4 v130, s[68:69]
	s_waitcnt vmcnt(6) lgkmcnt(0)
	s_barrier
	v_mfma_f32_16x16x32_bf16 v[62:65], v[136:139], v[168:171], v[62:65]
	v_mfma_f32_16x16x32_bf16 v[58:61], v[144:147], v[168:171], v[58:61]
	v_mfma_f32_16x16x32_bf16 v[46:49], v[136:139], v[176:179], v[46:49]
	v_mfma_f32_16x16x32_bf16 v[42:45], v[144:147], v[176:179], v[42:45]
	v_mfma_f32_16x16x32_bf16 v[30:33], v[136:139], v[184:187], v[30:33]
	v_mfma_f32_16x16x32_bf16 v[26:29], v[144:147], v[184:187], v[26:29]
	v_mfma_f32_16x16x32_bf16 v[14:17], v[136:139], v[192:195], v[14:17]
	v_mfma_f32_16x16x32_bf16 v[10:13], v[144:147], v[192:195], v[10:13]
	v_mfma_f32_16x16x32_bf16 v[62:65], v[140:143], v[172:175], v[62:65]
	v_mfma_f32_16x16x32_bf16 v[58:61], v[148:151], v[172:175], v[58:61]
	v_mfma_f32_16x16x32_bf16 v[46:49], v[140:143], v[180:183], v[46:49]
	v_mfma_f32_16x16x32_bf16 v[42:45], v[148:151], v[180:183], v[42:45]
	v_mfma_f32_16x16x32_bf16 v[30:33], v[140:143], v[188:191], v[30:33]
	v_mfma_f32_16x16x32_bf16 v[26:29], v[148:151], v[188:191], v[26:29]
	v_mfma_f32_16x16x32_bf16 v[14:17], v[140:143], v[196:199], v[14:17]
	v_mfma_f32_16x16x32_bf16 v[10:13], v[148:151], v[196:199], v[10:13]
	v_mfma_f32_16x16x32_bf16 v[54:57], v[224:227], v[168:171], v[54:57]
	v_mfma_f32_16x16x32_bf16 v[50:53], v[232:235], v[168:171], v[50:53]
	v_mfma_f32_16x16x32_bf16 v[38:41], v[224:227], v[176:179], v[38:41]
	v_mfma_f32_16x16x32_bf16 v[34:37], v[232:235], v[176:179], v[34:37]
	v_mfma_f32_16x16x32_bf16 v[22:25], v[224:227], v[184:187], v[22:25]
	v_mfma_f32_16x16x32_bf16 v[18:21], v[232:235], v[184:187], v[18:21]
	v_mfma_f32_16x16x32_bf16 v[6:9], v[224:227], v[192:195], v[6:9]
	v_mfma_f32_16x16x32_bf16 v[2:5], v[232:235], v[192:195], v[2:5]
	v_mfma_f32_16x16x32_bf16 v[54:57], v[228:231], v[172:175], v[54:57]
	v_mfma_f32_16x16x32_bf16 v[50:53], v[236:239], v[172:175], v[50:53]
	v_mfma_f32_16x16x32_bf16 v[38:41], v[228:231], v[180:183], v[38:41]
	v_mfma_f32_16x16x32_bf16 v[34:37], v[236:239], v[180:183], v[34:37]
	v_mfma_f32_16x16x32_bf16 v[22:25], v[228:231], v[188:191], v[22:25]
	v_mfma_f32_16x16x32_bf16 v[18:21], v[236:239], v[188:191], v[18:21]
	v_mfma_f32_16x16x32_bf16 v[6:9], v[228:231], v[196:199], v[6:9]
	v_mfma_f32_16x16x32_bf16 v[2:5], v[236:239], v[196:199], v[2:5]
	s_barrier
	s_add_i32 s68, 0, 0x18000
	v_add_u32_e32 v148, s68, v153
	ds_read_b128 v[136:139], v148
	ds_read_b128 v[140:143], v148 offset:1024
	ds_read_b128 v[144:147], v148 offset:2048
	ds_read_b128 v[148:151], v148 offset:3072
	s_add_u32 s52, s52, 0x80000
	s_addc_u32 s53, s53, 0
	ds_read_b128 v[168:171], v155 offset:32768
	ds_read_b128 v[172:175], v155 offset:33792
	ds_read_b128 v[176:179], v155 offset:34816
	ds_read_b128 v[180:183], v155 offset:35840
	ds_read_b128 v[184:187], v155 offset:36864
	ds_read_b128 v[188:191], v155 offset:37888
	ds_read_b128 v[192:195], v155 offset:38912
	ds_read_b128 v[196:199], v155 offset:39936
	s_mov_b32 m0, s57
	s_nop 0
	global_load_lds_dwordx4 v0, s[52:53]
	s_mov_b32 m0, s58
	s_nop 0
	global_load_lds_dwordx4 v130, s[52:53]
	s_add_i32 s52, 0, 0x1c000
	s_add_i32 s53, s68, s54
	v_add_u32_e32 v161, s52, v153
	ds_read_b128 v[224:227], v161
	ds_read_b128 v[228:231], v161 offset:1024
	ds_read_b128 v[232:235], v161 offset:2048
	ds_read_b128 v[236:239], v161 offset:3072
	s_waitcnt lgkmcnt(0)
	s_barrier
	v_mfma_f32_16x16x32_bf16 v[126:129], v[136:139], v[168:171], v[126:129]
	v_mfma_f32_16x16x32_bf16 v[122:125], v[144:147], v[168:171], v[122:125]
	v_mfma_f32_16x16x32_bf16 v[110:113], v[136:139], v[176:179], v[110:113]
	v_mfma_f32_16x16x32_bf16 v[106:109], v[144:147], v[176:179], v[106:109]
	v_mfma_f32_16x16x32_bf16 v[94:97], v[136:139], v[184:187], v[94:97]
	v_mfma_f32_16x16x32_bf16 v[90:93], v[144:147], v[184:187], v[90:93]
	v_mfma_f32_16x16x32_bf16 v[78:81], v[136:139], v[192:195], v[78:81]
	v_mfma_f32_16x16x32_bf16 v[74:77], v[144:147], v[192:195], v[74:77]
	v_mfma_f32_16x16x32_bf16 v[126:129], v[140:143], v[172:175], v[126:129]
	v_mfma_f32_16x16x32_bf16 v[122:125], v[148:151], v[172:175], v[122:125]
	v_mfma_f32_16x16x32_bf16 v[110:113], v[140:143], v[180:183], v[110:113]
	v_mfma_f32_16x16x32_bf16 v[106:109], v[148:151], v[180:183], v[106:109]
	v_mfma_f32_16x16x32_bf16 v[94:97], v[140:143], v[188:191], v[94:97]
	v_mfma_f32_16x16x32_bf16 v[90:93], v[148:151], v[188:191], v[90:93]
	v_mfma_f32_16x16x32_bf16 v[78:81], v[140:143], v[196:199], v[78:81]
	v_mfma_f32_16x16x32_bf16 v[74:77], v[148:151], v[196:199], v[74:77]
	v_mfma_f32_16x16x32_bf16 v[118:121], v[224:227], v[168:171], v[118:121]
	v_mfma_f32_16x16x32_bf16 v[114:117], v[232:235], v[168:171], v[114:117]
	v_mfma_f32_16x16x32_bf16 v[102:105], v[224:227], v[176:179], v[102:105]
	v_mfma_f32_16x16x32_bf16 v[98:101], v[232:235], v[176:179], v[98:101]
	v_mfma_f32_16x16x32_bf16 v[86:89], v[224:227], v[184:187], v[86:89]
	v_mfma_f32_16x16x32_bf16 v[82:85], v[232:235], v[184:187], v[82:85]
	v_mfma_f32_16x16x32_bf16 v[70:73], v[224:227], v[192:195], v[70:73]
	v_mfma_f32_16x16x32_bf16 v[66:69], v[232:235], v[192:195], v[66:69]
	v_mfma_f32_16x16x32_bf16 v[118:121], v[228:231], v[172:175], v[118:121]
	v_mfma_f32_16x16x32_bf16 v[114:117], v[236:239], v[172:175], v[114:117]
	v_mfma_f32_16x16x32_bf16 v[102:105], v[228:231], v[180:183], v[102:105]
	v_mfma_f32_16x16x32_bf16 v[98:101], v[236:239], v[180:183], v[98:101]
	v_mfma_f32_16x16x32_bf16 v[86:89], v[228:231], v[188:191], v[86:89]
	v_mfma_f32_16x16x32_bf16 v[82:85], v[236:239], v[188:191], v[82:85]
	v_mfma_f32_16x16x32_bf16 v[70:73], v[228:231], v[196:199], v[70:73]
	v_mfma_f32_16x16x32_bf16 v[66:69], v[236:239], v[196:199], v[66:69]
	s_barrier
	s_mov_b32 m0, s59
	ds_read_b128 v[168:171], v155 offset:49152
	ds_read_b128 v[172:175], v155 offset:50176
	ds_read_b128 v[176:179], v155 offset:51200
	ds_read_b128 v[180:183], v155 offset:52224
	ds_read_b128 v[184:187], v155 offset:53248
	ds_read_b128 v[188:191], v155 offset:54272
	ds_read_b128 v[192:195], v155 offset:55296
	ds_read_b128 v[196:199], v155 offset:56320
	global_load_lds_dwordx4 v0, s[78:79]
	s_mov_b32 m0, s60
	s_nop 0
	global_load_lds_dwordx4 v130, s[78:79]
	s_mov_b32 m0, s53
	s_nop 0
	global_load_lds_dwordx4 v0, s[76:77]
	s_add_i32 m0, s53, 0x2000
	s_nop 0
	global_load_lds_dwordx4 v130, s[76:77]
	s_add_u32 s50, s50, 0x80080
	s_addc_u32 s51, s51, 0
	s_add_i32 s52, s52, s54
	s_mov_b32 m0, s52
	s_nop 0
	global_load_lds_dwordx4 v0, s[50:51]
	s_add_i32 m0, s52, 0x2000
	s_nop 0
	global_load_lds_dwordx4 v130, s[50:51]
	s_waitcnt vmcnt(6) lgkmcnt(0)
	s_barrier
	v_mfma_f32_16x16x32_bf16 v[62:65], v[136:139], v[168:171], v[62:65]
	v_mfma_f32_16x16x32_bf16 v[58:61], v[144:147], v[168:171], v[58:61]
	v_mfma_f32_16x16x32_bf16 v[46:49], v[136:139], v[176:179], v[46:49]
	v_mfma_f32_16x16x32_bf16 v[42:45], v[144:147], v[176:179], v[42:45]
	v_mfma_f32_16x16x32_bf16 v[30:33], v[136:139], v[184:187], v[30:33]
	v_mfma_f32_16x16x32_bf16 v[26:29], v[144:147], v[184:187], v[26:29]
	v_mfma_f32_16x16x32_bf16 v[14:17], v[136:139], v[192:195], v[14:17]
	v_mfma_f32_16x16x32_bf16 v[10:13], v[144:147], v[192:195], v[10:13]
	v_mfma_f32_16x16x32_bf16 v[62:65], v[140:143], v[172:175], v[62:65]
	v_mfma_f32_16x16x32_bf16 v[58:61], v[148:151], v[172:175], v[58:61]
	v_mfma_f32_16x16x32_bf16 v[46:49], v[140:143], v[180:183], v[46:49]
	v_mfma_f32_16x16x32_bf16 v[42:45], v[148:151], v[180:183], v[42:45]
	v_mfma_f32_16x16x32_bf16 v[30:33], v[140:143], v[188:191], v[30:33]
	v_mfma_f32_16x16x32_bf16 v[26:29], v[148:151], v[188:191], v[26:29]
	v_mfma_f32_16x16x32_bf16 v[14:17], v[140:143], v[196:199], v[14:17]
	v_mfma_f32_16x16x32_bf16 v[10:13], v[148:151], v[196:199], v[10:13]
	v_mfma_f32_16x16x32_bf16 v[54:57], v[224:227], v[168:171], v[54:57]
	v_mfma_f32_16x16x32_bf16 v[50:53], v[232:235], v[168:171], v[50:53]
	v_mfma_f32_16x16x32_bf16 v[38:41], v[224:227], v[176:179], v[38:41]
	v_mfma_f32_16x16x32_bf16 v[34:37], v[232:235], v[176:179], v[34:37]
	v_mfma_f32_16x16x32_bf16 v[22:25], v[224:227], v[184:187], v[22:25]
	v_mfma_f32_16x16x32_bf16 v[18:21], v[232:235], v[184:187], v[18:21]
	v_mfma_f32_16x16x32_bf16 v[6:9], v[224:227], v[192:195], v[6:9]
	v_mfma_f32_16x16x32_bf16 v[2:5], v[232:235], v[192:195], v[2:5]
	v_mfma_f32_16x16x32_bf16 v[54:57], v[228:231], v[172:175], v[54:57]
	v_mfma_f32_16x16x32_bf16 v[50:53], v[236:239], v[172:175], v[50:53]
	v_mfma_f32_16x16x32_bf16 v[38:41], v[228:231], v[180:183], v[38:41]
	v_mfma_f32_16x16x32_bf16 v[34:37], v[236:239], v[180:183], v[34:37]
	v_mfma_f32_16x16x32_bf16 v[22:25], v[228:231], v[188:191], v[22:25]
	v_mfma_f32_16x16x32_bf16 v[18:21], v[236:239], v[188:191], v[18:21]
	v_mfma_f32_16x16x32_bf16 v[6:9], v[228:231], v[196:199], v[6:9]
	v_mfma_f32_16x16x32_bf16 v[2:5], v[236:239], v[196:199], v[2:5]
	s_barrier
	s_add_u32 s0, s0, 0x100
	s_addc_u32 s1, s1, 0
	s_add_u32 s13, s13, 0x100
	s_addc_u32 s66, s66, 0
	s_mov_b32 s50, s67
	s_cmp_ge_i32 s67, s41
	s_cbranch_scc0 .LBB0_282
	s_cmp_eq_u32 s63, 2
	s_cbranch_scc1 .Lepi6_orig
	v_readlane_b32 s90, v255, 17
	v_readlane_b32 s91, v255, 18
	v_readlane_b32 s96, v255, 19
	v_readlane_b32 s97, v255, 20
	v_readlane_b32 s8, v255, 25
	v_readlane_b32 s9, v255, 26
	v_readlane_b32 s68, v253, 58
	v_readlane_b32 s69, v253, 59
	v_lshl_or_b32 v156, s64, 8, v154
	v_lshlrev_b32_e32 v156, 2, v156
	v_lshl_add_u32 v157, v152, 13, v156
	s_lshl_b32 s72, s65, 21
	s_add_u32 s74, s68, s72
	s_addc_u32 s75, s69, 0
	s_add_u32 s76, s22, s72
	s_addc_u32 s77, s23, 0
	s_lshr_b32 s73, s65, 3
	s_mul_i32 s73, s73, 0xc000
	s_add_u32 s73, s73, 0x4000
	s_add_u32 s70, s90, s73
	s_addc_u32 s71, s91, 0
	global_load_dwordx4 v[140:143], v156, s[70:71]
	global_load_dwordx4 v[144:147], v156, s[70:71] offset:64
	global_load_dwordx4 v[148:151], v156, s[70:71] offset:512
	global_load_dwordx4 v[168:171], v156, s[70:71] offset:576
	global_load_dwordx4 v[224:227], v157, s[74:75] nt
	global_load_dwordx4 v[228:231], v157, s[74:75] offset:64 nt
	global_load_dwordx4 v[232:235], v157, s[74:75] offset:512 nt
	global_load_dwordx4 v[236:239], v157, s[74:75] offset:576 nt
	s_add_u32 s74, s74, 0x20000
	s_addc_u32 s75, s75, 0
	global_load_dwordx4 v[240:243], v157, s[74:75] nt
	global_load_dwordx4 v[244:247], v157, s[74:75] offset:64 nt
	s_waitcnt vmcnt(5)
	v_pk_fma_f32 v[128:129], v[128:129], v[142:143], v[226:227]
	v_pk_fma_f32 v[126:127], v[126:127], v[140:141], v[224:225]
	global_store_dwordx4 v157, v[126:129], s[76:77]
	global_load_dwordx4 v[224:227], v157, s[74:75] offset:512 nt
	s_waitcnt vmcnt(6)
	v_pk_fma_f32 v[124:125], v[124:125], v[146:147], v[230:231]
	v_pk_fma_f32 v[122:123], v[122:123], v[144:145], v[228:229]
	global_store_dwordx4 v157, v[122:125], s[76:77] offset:64
	global_load_dwordx4 v[228:231], v157, s[74:75] offset:576 nt
	s_waitcnt vmcnt(7)
	v_pk_fma_f32 v[120:121], v[120:121], v[150:151], v[234:235]
	v_pk_fma_f32 v[118:119], v[118:119], v[148:149], v[232:233]
	global_store_dwordx4 v157, v[118:121], s[76:77] offset:512
	s_add_u32 s74, s74, 0x20000
	s_addc_u32 s75, s75, 0
	global_load_dwordx4 v[232:235], v157, s[74:75] nt
	s_waitcnt vmcnt(8)
	v_pk_fma_f32 v[116:117], v[116:117], v[170:171], v[238:239]
	v_pk_fma_f32 v[114:115], v[114:115], v[168:169], v[236:237]
	global_store_dwordx4 v157, v[114:117], s[76:77] offset:576
	global_load_dwordx4 v[236:239], v157, s[74:75] offset:64 nt
	s_add_u32 s76, s76, 0x20000
	s_addc_u32 s77, s77, 0
	s_waitcnt vmcnt(9)
	v_pk_fma_f32 v[112:113], v[112:113], v[142:143], v[242:243]
	v_pk_fma_f32 v[110:111], v[110:111], v[140:141], v[240:241]
	global_store_dwordx4 v157, v[110:113], s[76:77]
	global_load_dwordx4 v[240:243], v157, s[74:75] offset:512 nt
	s_waitcnt vmcnt(10)
	v_pk_fma_f32 v[108:109], v[108:109], v[146:147], v[246:247]
	v_pk_fma_f32 v[106:107], v[106:107], v[144:145], v[244:245]
	global_store_dwordx4 v157, v[106:109], s[76:77] offset:64
	global_load_dwordx4 v[244:247], v157, s[74:75] offset:576 nt
	s_waitcnt vmcnt(10)
	v_pk_fma_f32 v[104:105], v[104:105], v[150:151], v[226:227]
	v_pk_fma_f32 v[102:103], v[102:103], v[148:149], v[224:225]
	global_store_dwordx4 v157, v[102:105], s[76:77] offset:512
	s_add_u32 s74, s74, 0x20000
	s_addc_u32 s75, s75, 0
	global_load_dwordx4 v[224:227], v157, s[74:75] nt
	s_waitcnt vmcnt(10)
	v_pk_fma_f32 v[100:101], v[100:101], v[170:171], v[230:231]
	v_pk_fma_f32 v[98:99], v[98:99], v[168:169], v[228:229]
	global_store_dwordx4 v157, v[98:101], s[76:77] offset:576
	global_load_dwordx4 v[228:231], v157, s[74:75] offset:64 nt
	s_add_u32 s76, s76, 0x20000
	s_addc_u32 s77, s77, 0
	s_waitcnt vmcnt(10)
	v_pk_fma_f32 v[96:97], v[96:97], v[142:143], v[234:235]
	v_pk_fma_f32 v[94:95], v[94:95], v[140:141], v[232:233]
	global_store_dwordx4 v157, v[94:97], s[76:77]
	global_load_dwordx4 v[232:235], v157, s[74:75] offset:512 nt
	s_waitcnt vmcnt(10)
	v_pk_fma_f32 v[92:93], v[92:93], v[146:147], v[238:239]
	v_pk_fma_f32 v[90:91], v[90:91], v[144:145], v[236:237]
	global_store_dwordx4 v157, v[90:93], s[76:77] offset:64
	global_load_dwordx4 v[236:239], v157, s[74:75] offset:576 nt
	s_waitcnt vmcnt(10)
	v_pk_fma_f32 v[88:89], v[88:89], v[150:151], v[242:243]
	v_pk_fma_f32 v[86:87], v[86:87], v[148:149], v[240:241]
	global_store_dwordx4 v157, v[86:89], s[76:77] offset:512
	s_add_u32 s74, s74, 0xa0000
	s_addc_u32 s75, s75, 0
	global_load_dwordx4 v[240:243], v157, s[74:75] nt
	s_waitcnt vmcnt(10)
	v_pk_fma_f32 v[84:85], v[84:85], v[170:171], v[246:247]
	v_pk_fma_f32 v[82:83], v[82:83], v[168:169], v[244:245]
	global_store_dwordx4 v157, v[82:85], s[76:77] offset:576
	global_load_dwordx4 v[244:247], v157, s[74:75] offset:64 nt
	s_add_u32 s76, s76, 0x20000
	s_addc_u32 s77, s77, 0
	s_waitcnt vmcnt(10)
	v_pk_fma_f32 v[80:81], v[80:81], v[142:143], v[226:227]
	v_pk_fma_f32 v[78:79], v[78:79], v[140:141], v[224:225]
	global_store_dwordx4 v157, v[78:81], s[76:77]
	global_load_dwordx4 v[224:227], v157, s[74:75] offset:512 nt
	s_waitcnt vmcnt(10)
	v_pk_fma_f32 v[76:77], v[76:77], v[146:147], v[230:231]
	v_pk_fma_f32 v[74:75], v[74:75], v[144:145], v[228:229]
	global_store_dwordx4 v157, v[74:77], s[76:77] offset:64
	global_load_dwordx4 v[228:231], v157, s[74:75] offset:576 nt
	s_waitcnt vmcnt(10)
	v_pk_fma_f32 v[72:73], v[72:73], v[150:151], v[234:235]
	v_pk_fma_f32 v[70:71], v[70:71], v[148:149], v[232:233]
	global_store_dwordx4 v157, v[70:73], s[76:77] offset:512
	s_add_u32 s74, s74, 0x20000
	s_addc_u32 s75, s75, 0
	global_load_dwordx4 v[232:235], v157, s[74:75] nt
	s_waitcnt vmcnt(10)
	v_pk_fma_f32 v[68:69], v[68:69], v[170:171], v[238:239]
	v_pk_fma_f32 v[66:67], v[66:67], v[168:169], v[236:237]
	global_store_dwordx4 v157, v[66:69], s[76:77] offset:576
	global_load_dwordx4 v[236:239], v157, s[74:75] offset:64 nt
	s_add_u32 s76, s76, 0xa0000
	s_addc_u32 s77, s77, 0
	s_waitcnt vmcnt(10)
	v_pk_fma_f32 v[64:65], v[64:65], v[142:143], v[242:243]
	v_pk_fma_f32 v[62:63], v[62:63], v[140:141], v[240:241]
	global_store_dwordx4 v157, v[62:65], s[76:77]
	global_load_dwordx4 v[240:243], v157, s[74:75] offset:512 nt
	s_waitcnt vmcnt(10)
	v_pk_fma_f32 v[60:61], v[60:61], v[146:147], v[246:247]
	v_pk_fma_f32 v[58:59], v[58:59], v[144:145], v[244:245]
	global_store_dwordx4 v157, v[58:61], s[76:77] offset:64
	global_load_dwordx4 v[244:247], v157, s[74:75] offset:576 nt
	s_waitcnt vmcnt(10)
	v_pk_fma_f32 v[56:57], v[56:57], v[150:151], v[226:227]
	v_pk_fma_f32 v[54:55], v[54:55], v[148:149], v[224:225]
	global_store_dwordx4 v157, v[54:57], s[76:77] offset:512
	s_add_u32 s74, s74, 0x20000
	s_addc_u32 s75, s75, 0
	global_load_dwordx4 v[224:227], v157, s[74:75] nt
	s_waitcnt vmcnt(10)
	v_pk_fma_f32 v[52:53], v[52:53], v[170:171], v[230:231]
	v_pk_fma_f32 v[50:51], v[50:51], v[168:169], v[228:229]
	global_store_dwordx4 v157, v[50:53], s[76:77] offset:576
	global_load_dwordx4 v[228:231], v157, s[74:75] offset:64 nt
	s_add_u32 s76, s76, 0x20000
	s_addc_u32 s77, s77, 0
	s_waitcnt vmcnt(10)
	v_pk_fma_f32 v[48:49], v[48:49], v[142:143], v[234:235]
	v_pk_fma_f32 v[46:47], v[46:47], v[140:141], v[232:233]
	global_store_dwordx4 v157, v[46:49], s[76:77]
	global_load_dwordx4 v[232:235], v157, s[74:75] offset:512 nt
	s_waitcnt vmcnt(10)
	v_pk_fma_f32 v[44:45], v[44:45], v[146:147], v[238:239]
	v_pk_fma_f32 v[42:43], v[42:43], v[144:145], v[236:237]
	global_store_dwordx4 v157, v[42:45], s[76:77] offset:64
	global_load_dwordx4 v[236:239], v157, s[74:75] offset:576 nt
	s_waitcnt vmcnt(10)
	v_pk_fma_f32 v[40:41], v[40:41], v[150:151], v[242:243]
	v_pk_fma_f32 v[38:39], v[38:39], v[148:149], v[240:241]
	global_store_dwordx4 v157, v[38:41], s[76:77] offset:512
	s_add_u32 s74, s74, 0x20000
	s_addc_u32 s75, s75, 0
	global_load_dwordx4 v[240:243], v157, s[74:75] nt
	s_waitcnt vmcnt(10)
	v_pk_fma_f32 v[36:37], v[36:37], v[170:171], v[246:247]
	v_pk_fma_f32 v[34:35], v[34:35], v[168:169], v[244:245]
	global_store_dwordx4 v157, v[34:37], s[76:77] offset:576
	global_load_dwordx4 v[244:247], v157, s[74:75] offset:64 nt
	s_add_u32 s76, s76, 0x20000
	s_addc_u32 s77, s77, 0
	s_waitcnt vmcnt(10)
	v_pk_fma_f32 v[32:33], v[32:33], v[142:143], v[226:227]
	v_pk_fma_f32 v[30:31], v[30:31], v[140:141], v[224:225]
	global_store_dwordx4 v157, v[30:33], s[76:77]
	global_load_dwordx4 v[224:227], v157, s[74:75] offset:512 nt
	s_waitcnt vmcnt(10)
	v_pk_fma_f32 v[28:29], v[28:29], v[146:147], v[230:231]
	v_pk_fma_f32 v[26:27], v[26:27], v[144:145], v[228:229]
	global_store_dwordx4 v157, v[26:29], s[76:77] offset:64
	global_load_dwordx4 v[228:231], v157, s[74:75] offset:576 nt
	s_waitcnt vmcnt(10)
	v_pk_fma_f32 v[24:25], v[24:25], v[150:151], v[234:235]
	v_pk_fma_f32 v[22:23], v[22:23], v[148:149], v[232:233]
	global_store_dwordx4 v157, v[22:25], s[76:77] offset:512
	s_waitcnt vmcnt(9)
	v_pk_fma_f32 v[20:21], v[20:21], v[170:171], v[238:239]
	v_pk_fma_f32 v[18:19], v[18:19], v[168:169], v[236:237]
	global_store_dwordx4 v157, v[18:21], s[76:77] offset:576
	s_add_u32 s76, s76, 0x20000
	s_addc_u32 s77, s77, 0
	s_waitcnt vmcnt(8)
	v_pk_fma_f32 v[16:17], v[16:17], v[142:143], v[242:243]
	v_pk_fma_f32 v[14:15], v[14:15], v[140:141], v[240:241]
	global_store_dwordx4 v157, v[14:17], s[76:77]
	s_waitcnt vmcnt(7)
	v_pk_fma_f32 v[12:13], v[12:13], v[146:147], v[246:247]
	v_pk_fma_f32 v[10:11], v[10:11], v[144:145], v[244:245]
	global_store_dwordx4 v157, v[10:13], s[76:77] offset:64
	s_waitcnt vmcnt(6)
	v_pk_fma_f32 v[8:9], v[8:9], v[150:151], v[226:227]
	v_pk_fma_f32 v[6:7], v[6:7], v[148:149], v[224:225]
	global_store_dwordx4 v157, v[6:9], s[76:77] offset:512
	s_waitcnt vmcnt(5)
	v_pk_fma_f32 v[4:5], v[4:5], v[170:171], v[230:231]
	v_pk_fma_f32 v[2:3], v[2:3], v[168:169], v[228:229]
	global_store_dwordx4 v157, v[2:5], s[76:77] offset:576
	s_branch .LBB0_269

.LBB0_572:
	s_add_u32 s41, s46, 0xfff80080
	s_addc_u32 s48, s47, -1
	s_add_i32 s64, 0, 0x10000
	v_add_u32_e32 v156, s64, v141
	ds_read_b128 v[144:147], v156
	ds_read_b128 v[148:151], v156 offset:1024
	ds_read_b128 v[152:155], v156 offset:2048
	ds_read_b128 v[168:171], v156 offset:3072
	s_cmp_eq_u32 s39, 28
	s_cselect_b32 s51, s43, s48
	s_cselect_b32 s50, s42, s41
	s_cselect_b32 s49, s45, s13
	s_cselect_b32 s48, s44, s12
	ds_read_b128 v[172:175], v143
	ds_read_b128 v[176:179], v143 offset:1024
	ds_read_b128 v[180:183], v143 offset:2048
	ds_read_b128 v[184:187], v143 offset:3072
	ds_read_b128 v[188:191], v143 offset:4096
	ds_read_b128 v[192:195], v143 offset:5120
	ds_read_b128 v[196:199], v143 offset:6144
	ds_read_b128 v[224:227], v143 offset:7168
	s_add_i32 m0, s54, 0xc000
	s_nop 0
	global_load_lds_dwordx4 v136, s[46:47]
	s_add_i32 m0, s54, 0xe000
	s_nop 0
	global_load_lds_dwordx4 v138, s[46:47]
	s_add_i32 s41, 0, 0x14000
	v_add_u32_e32 v156, s41, v141
	s_add_i32 s64, s64, s53
	ds_read_b128 v[228:231], v156
	ds_read_b128 v[232:235], v156 offset:1024
	ds_read_b128 v[236:239], v156 offset:2048
	ds_read_b128 v[240:243], v156 offset:3072
	s_waitcnt lgkmcnt(0)
	s_barrier
	v_mfma_f32_16x16x32_bf16 v[126:129], v[144:147], v[172:175], v[126:129]
	v_mfma_f32_16x16x32_bf16 v[122:125], v[152:155], v[172:175], v[122:125]
	v_mfma_f32_16x16x32_bf16 v[118:121], v[144:147], v[180:183], v[118:121]
	v_mfma_f32_16x16x32_bf16 v[114:117], v[152:155], v[180:183], v[114:117]
	v_mfma_f32_16x16x32_bf16 v[102:105], v[144:147], v[188:191], v[102:105]
	v_mfma_f32_16x16x32_bf16 v[98:101], v[152:155], v[188:191], v[98:101]
	v_mfma_f32_16x16x32_bf16 v[86:89], v[144:147], v[196:199], v[86:89]
	v_mfma_f32_16x16x32_bf16 v[82:85], v[152:155], v[196:199], v[82:85]
	v_mfma_f32_16x16x32_bf16 v[126:129], v[148:151], v[176:179], v[126:129]
	v_mfma_f32_16x16x32_bf16 v[122:125], v[168:171], v[176:179], v[122:125]
	v_mfma_f32_16x16x32_bf16 v[118:121], v[148:151], v[184:187], v[118:121]
	v_mfma_f32_16x16x32_bf16 v[114:117], v[168:171], v[184:187], v[114:117]
	v_mfma_f32_16x16x32_bf16 v[102:105], v[148:151], v[192:195], v[102:105]
	v_mfma_f32_16x16x32_bf16 v[98:101], v[168:171], v[192:195], v[98:101]
	v_mfma_f32_16x16x32_bf16 v[86:89], v[148:151], v[224:227], v[86:89]
	v_mfma_f32_16x16x32_bf16 v[82:85], v[168:171], v[224:227], v[82:85]
	v_mfma_f32_16x16x32_bf16 v[110:113], v[228:231], v[172:175], v[110:113]
	v_mfma_f32_16x16x32_bf16 v[106:109], v[236:239], v[172:175], v[106:109]
	v_mfma_f32_16x16x32_bf16 v[94:97], v[228:231], v[180:183], v[94:97]
	v_mfma_f32_16x16x32_bf16 v[90:93], v[236:239], v[180:183], v[90:93]
	v_mfma_f32_16x16x32_bf16 v[78:81], v[228:231], v[188:191], v[78:81]
	v_mfma_f32_16x16x32_bf16 v[74:77], v[236:239], v[188:191], v[74:77]
	v_mfma_f32_16x16x32_bf16 v[70:73], v[228:231], v[196:199], v[70:73]
	v_mfma_f32_16x16x32_bf16 v[66:69], v[236:239], v[196:199], v[66:69]
	v_mfma_f32_16x16x32_bf16 v[110:113], v[232:235], v[176:179], v[110:113]
	v_mfma_f32_16x16x32_bf16 v[106:109], v[240:243], v[176:179], v[106:109]
	v_mfma_f32_16x16x32_bf16 v[94:97], v[232:235], v[184:187], v[94:97]
	v_mfma_f32_16x16x32_bf16 v[90:93], v[240:243], v[184:187], v[90:93]
	v_mfma_f32_16x16x32_bf16 v[78:81], v[232:235], v[192:195], v[78:81]
	v_mfma_f32_16x16x32_bf16 v[74:77], v[240:243], v[192:195], v[74:77]
	v_mfma_f32_16x16x32_bf16 v[70:73], v[232:235], v[224:227], v[70:73]
	v_mfma_f32_16x16x32_bf16 v[66:69], v[240:243], v[224:227], v[66:69]
	s_barrier
	s_mov_b32 m0, s54
	s_add_u32 s78, s50, s94
	s_addc_u32 s79, s51, s95
	ds_read_b128 v[172:175], v143 offset:16384
	ds_read_b128 v[176:179], v143 offset:17408
	ds_read_b128 v[180:183], v143 offset:18432
	ds_read_b128 v[184:187], v143 offset:19456
	ds_read_b128 v[188:191], v143 offset:20480
	ds_read_b128 v[192:195], v143 offset:21504
	ds_read_b128 v[196:199], v143 offset:22528
	ds_read_b128 v[224:227], v143 offset:23552
	global_load_lds_dwordx4 v130, s[50:51]
	s_mov_b32 m0, s55
	s_nop 0
	global_load_lds_dwordx4 v132, s[50:51]
	s_add_u32 s76, s48, s94
	s_addc_u32 s77, s49, s95
	s_mov_b32 m0, s64
	s_nop 0
	global_load_lds_dwordx4 v0, s[48:49]
	s_add_i32 m0, s64, 0x2000
	s_nop 0
	global_load_lds_dwordx4 v134, s[48:49]
	s_add_u32 s64, s48, 0x80000
	s_addc_u32 s65, s49, 0
	s_add_i32 s41, s41, s53
	s_mov_b32 m0, s41
	s_nop 0
	global_load_lds_dwordx4 v0, s[64:65]
	s_add_i32 m0, s41, 0x2000
	s_nop 0
	global_load_lds_dwordx4 v134, s[64:65]
	s_waitcnt vmcnt(6) lgkmcnt(0)
	s_barrier
	v_mfma_f32_16x16x32_bf16 v[62:65], v[144:147], v[172:175], v[62:65]
	v_mfma_f32_16x16x32_bf16 v[58:61], v[152:155], v[172:175], v[58:61]
	v_mfma_f32_16x16x32_bf16 v[54:57], v[144:147], v[180:183], v[54:57]
	v_mfma_f32_16x16x32_bf16 v[50:53], v[152:155], v[180:183], v[50:53]
	v_mfma_f32_16x16x32_bf16 v[38:41], v[144:147], v[188:191], v[38:41]
	v_mfma_f32_16x16x32_bf16 v[34:37], v[152:155], v[188:191], v[34:37]
	v_mfma_f32_16x16x32_bf16 v[22:25], v[144:147], v[196:199], v[22:25]
	v_mfma_f32_16x16x32_bf16 v[18:21], v[152:155], v[196:199], v[18:21]
	v_mfma_f32_16x16x32_bf16 v[62:65], v[148:151], v[176:179], v[62:65]
	v_mfma_f32_16x16x32_bf16 v[58:61], v[168:171], v[176:179], v[58:61]
	v_mfma_f32_16x16x32_bf16 v[54:57], v[148:151], v[184:187], v[54:57]
	v_mfma_f32_16x16x32_bf16 v[50:53], v[168:171], v[184:187], v[50:53]
	v_mfma_f32_16x16x32_bf16 v[38:41], v[148:151], v[192:195], v[38:41]
	v_mfma_f32_16x16x32_bf16 v[34:37], v[168:171], v[192:195], v[34:37]
	v_mfma_f32_16x16x32_bf16 v[22:25], v[148:151], v[224:227], v[22:25]
	v_mfma_f32_16x16x32_bf16 v[18:21], v[168:171], v[224:227], v[18:21]
	v_mfma_f32_16x16x32_bf16 v[46:49], v[228:231], v[172:175], v[46:49]
	v_mfma_f32_16x16x32_bf16 v[42:45], v[236:239], v[172:175], v[42:45]
	v_mfma_f32_16x16x32_bf16 v[30:33], v[228:231], v[180:183], v[30:33]
	v_mfma_f32_16x16x32_bf16 v[26:29], v[236:239], v[180:183], v[26:29]
	v_mfma_f32_16x16x32_bf16 v[14:17], v[228:231], v[188:191], v[14:17]
	v_mfma_f32_16x16x32_bf16 v[10:13], v[236:239], v[188:191], v[10:13]
	v_mfma_f32_16x16x32_bf16 v[6:9], v[228:231], v[196:199], v[6:9]
	v_mfma_f32_16x16x32_bf16 v[2:5], v[236:239], v[196:199], v[2:5]
	v_mfma_f32_16x16x32_bf16 v[46:49], v[232:235], v[176:179], v[46:49]
	v_mfma_f32_16x16x32_bf16 v[42:45], v[240:243], v[176:179], v[42:45]
	v_mfma_f32_16x16x32_bf16 v[30:33], v[232:235], v[184:187], v[30:33]
	v_mfma_f32_16x16x32_bf16 v[26:29], v[240:243], v[184:187], v[26:29]
	v_mfma_f32_16x16x32_bf16 v[14:17], v[232:235], v[192:195], v[14:17]
	v_mfma_f32_16x16x32_bf16 v[10:13], v[240:243], v[192:195], v[10:13]
	v_mfma_f32_16x16x32_bf16 v[6:9], v[232:235], v[224:227], v[6:9]
	v_mfma_f32_16x16x32_bf16 v[2:5], v[240:243], v[224:227], v[2:5]
	s_barrier
	s_add_i32 s41, 0, 0x18000
	v_add_u32_e32 v161, s41, v141
	ds_read_b128 v[144:147], v161
	ds_read_b128 v[148:151], v161 offset:1024
	ds_read_b128 v[152:155], v161 offset:2048
	ds_read_b128 v[168:171], v161 offset:3072
	s_add_u32 s50, s50, 0x80000
	s_addc_u32 s51, s51, 0
	ds_read_b128 v[172:175], v143 offset:32768
	ds_read_b128 v[176:179], v143 offset:33792
	ds_read_b128 v[180:183], v143 offset:34816
	ds_read_b128 v[184:187], v143 offset:35840
	ds_read_b128 v[188:191], v143 offset:36864
	ds_read_b128 v[192:195], v143 offset:37888
	ds_read_b128 v[196:199], v143 offset:38912
	ds_read_b128 v[224:227], v143 offset:39936
	s_mov_b32 m0, s56
	s_nop 0
	global_load_lds_dwordx4 v130, s[50:51]
	s_mov_b32 m0, s57
	s_nop 0
	global_load_lds_dwordx4 v132, s[50:51]
	s_add_i32 s50, 0, 0x1c000
	s_add_i32 s41, s41, s53
	v_add_u32_e32 v161, s50, v141
	ds_read_b128 v[228:231], v161
	ds_read_b128 v[232:235], v161 offset:1024
	ds_read_b128 v[236:239], v161 offset:2048
	ds_read_b128 v[240:243], v161 offset:3072
	s_waitcnt lgkmcnt(0)
	s_barrier
	v_mfma_f32_16x16x32_bf16 v[126:129], v[144:147], v[172:175], v[126:129]
	v_mfma_f32_16x16x32_bf16 v[122:125], v[152:155], v[172:175], v[122:125]
	v_mfma_f32_16x16x32_bf16 v[118:121], v[144:147], v[180:183], v[118:121]
	v_mfma_f32_16x16x32_bf16 v[114:117], v[152:155], v[180:183], v[114:117]
	v_mfma_f32_16x16x32_bf16 v[102:105], v[144:147], v[188:191], v[102:105]
	v_mfma_f32_16x16x32_bf16 v[98:101], v[152:155], v[188:191], v[98:101]
	v_mfma_f32_16x16x32_bf16 v[86:89], v[144:147], v[196:199], v[86:89]
	v_mfma_f32_16x16x32_bf16 v[82:85], v[152:155], v[196:199], v[82:85]
	v_mfma_f32_16x16x32_bf16 v[126:129], v[148:151], v[176:179], v[126:129]
	v_mfma_f32_16x16x32_bf16 v[122:125], v[168:171], v[176:179], v[122:125]
	v_mfma_f32_16x16x32_bf16 v[118:121], v[148:151], v[184:187], v[118:121]
	v_mfma_f32_16x16x32_bf16 v[114:117], v[168:171], v[184:187], v[114:117]
	v_mfma_f32_16x16x32_bf16 v[102:105], v[148:151], v[192:195], v[102:105]
	v_mfma_f32_16x16x32_bf16 v[98:101], v[168:171], v[192:195], v[98:101]
	v_mfma_f32_16x16x32_bf16 v[86:89], v[148:151], v[224:227], v[86:89]
	v_mfma_f32_16x16x32_bf16 v[82:85], v[168:171], v[224:227], v[82:85]
	v_mfma_f32_16x16x32_bf16 v[110:113], v[228:231], v[172:175], v[110:113]
	v_mfma_f32_16x16x32_bf16 v[106:109], v[236:239], v[172:175], v[106:109]
	v_mfma_f32_16x16x32_bf16 v[94:97], v[228:231], v[180:183], v[94:97]
	v_mfma_f32_16x16x32_bf16 v[90:93], v[236:239], v[180:183], v[90:93]
	v_mfma_f32_16x16x32_bf16 v[78:81], v[228:231], v[188:191], v[78:81]
	v_mfma_f32_16x16x32_bf16 v[74:77], v[236:239], v[188:191], v[74:77]
	v_mfma_f32_16x16x32_bf16 v[70:73], v[228:231], v[196:199], v[70:73]
	v_mfma_f32_16x16x32_bf16 v[66:69], v[236:239], v[196:199], v[66:69]
	v_mfma_f32_16x16x32_bf16 v[110:113], v[232:235], v[176:179], v[110:113]
	v_mfma_f32_16x16x32_bf16 v[106:109], v[240:243], v[176:179], v[106:109]
	v_mfma_f32_16x16x32_bf16 v[94:97], v[232:235], v[184:187], v[94:97]
	v_mfma_f32_16x16x32_bf16 v[90:93], v[240:243], v[184:187], v[90:93]
	v_mfma_f32_16x16x32_bf16 v[78:81], v[232:235], v[192:195], v[78:81]
	v_mfma_f32_16x16x32_bf16 v[74:77], v[240:243], v[192:195], v[74:77]
	v_mfma_f32_16x16x32_bf16 v[70:73], v[232:235], v[224:227], v[70:73]
	v_mfma_f32_16x16x32_bf16 v[66:69], v[240:243], v[224:227], v[66:69]
	s_barrier
	s_mov_b32 m0, s59
	ds_read_b128 v[172:175], v143 offset:49152
	ds_read_b128 v[176:179], v143 offset:50176
	ds_read_b128 v[180:183], v143 offset:51200
	ds_read_b128 v[184:187], v143 offset:52224
	ds_read_b128 v[188:191], v143 offset:53248
	ds_read_b128 v[192:195], v143 offset:54272
	ds_read_b128 v[196:199], v143 offset:55296
	ds_read_b128 v[224:227], v143 offset:56320
	global_load_lds_dwordx4 v130, s[78:79]
	s_mov_b32 m0, s60
	s_nop 0
	global_load_lds_dwordx4 v132, s[78:79]
	s_mov_b32 m0, s41
	s_nop 0
	global_load_lds_dwordx4 v0, s[76:77]
	s_add_i32 m0, s41, 0x2000
	s_nop 0
	global_load_lds_dwordx4 v134, s[76:77]
	s_add_u32 s48, s48, 0x80080
	s_addc_u32 s49, s49, 0
	s_add_i32 s41, s50, s53
	s_mov_b32 m0, s41
	s_nop 0
	global_load_lds_dwordx4 v0, s[48:49]
	s_add_i32 m0, s41, 0x2000
	s_nop 0
	global_load_lds_dwordx4 v134, s[48:49]
	s_waitcnt vmcnt(6) lgkmcnt(0)
	s_barrier
	v_mfma_f32_16x16x32_bf16 v[62:65], v[144:147], v[172:175], v[62:65]
	v_mfma_f32_16x16x32_bf16 v[58:61], v[152:155], v[172:175], v[58:61]
	v_mfma_f32_16x16x32_bf16 v[54:57], v[144:147], v[180:183], v[54:57]
	v_mfma_f32_16x16x32_bf16 v[50:53], v[152:155], v[180:183], v[50:53]
	v_mfma_f32_16x16x32_bf16 v[38:41], v[144:147], v[188:191], v[38:41]
	v_mfma_f32_16x16x32_bf16 v[34:37], v[152:155], v[188:191], v[34:37]
	v_mfma_f32_16x16x32_bf16 v[22:25], v[144:147], v[196:199], v[22:25]
	v_mfma_f32_16x16x32_bf16 v[18:21], v[152:155], v[196:199], v[18:21]
	v_mfma_f32_16x16x32_bf16 v[62:65], v[148:151], v[176:179], v[62:65]
	v_mfma_f32_16x16x32_bf16 v[58:61], v[168:171], v[176:179], v[58:61]
	v_mfma_f32_16x16x32_bf16 v[54:57], v[148:151], v[184:187], v[54:57]
	v_mfma_f32_16x16x32_bf16 v[50:53], v[168:171], v[184:187], v[50:53]
	v_mfma_f32_16x16x32_bf16 v[38:41], v[148:151], v[192:195], v[38:41]
	v_mfma_f32_16x16x32_bf16 v[34:37], v[168:171], v[192:195], v[34:37]
	v_mfma_f32_16x16x32_bf16 v[22:25], v[148:151], v[224:227], v[22:25]
	v_mfma_f32_16x16x32_bf16 v[18:21], v[168:171], v[224:227], v[18:21]
	v_mfma_f32_16x16x32_bf16 v[46:49], v[228:231], v[172:175], v[46:49]
	v_mfma_f32_16x16x32_bf16 v[42:45], v[236:239], v[172:175], v[42:45]
	v_mfma_f32_16x16x32_bf16 v[30:33], v[228:231], v[180:183], v[30:33]
	v_mfma_f32_16x16x32_bf16 v[26:29], v[236:239], v[180:183], v[26:29]
	v_mfma_f32_16x16x32_bf16 v[14:17], v[228:231], v[188:191], v[14:17]
	v_mfma_f32_16x16x32_bf16 v[10:13], v[236:239], v[188:191], v[10:13]
	v_mfma_f32_16x16x32_bf16 v[6:9], v[228:231], v[196:199], v[6:9]
	v_mfma_f32_16x16x32_bf16 v[2:5], v[236:239], v[196:199], v[2:5]
	v_mfma_f32_16x16x32_bf16 v[46:49], v[232:235], v[176:179], v[46:49]
	v_mfma_f32_16x16x32_bf16 v[42:45], v[240:243], v[176:179], v[42:45]
	v_mfma_f32_16x16x32_bf16 v[30:33], v[232:235], v[184:187], v[30:33]
	v_mfma_f32_16x16x32_bf16 v[26:29], v[240:243], v[184:187], v[26:29]
	v_mfma_f32_16x16x32_bf16 v[14:17], v[232:235], v[192:195], v[14:17]
	v_mfma_f32_16x16x32_bf16 v[10:13], v[240:243], v[192:195], v[10:13]
	v_mfma_f32_16x16x32_bf16 v[6:9], v[232:235], v[224:227], v[6:9]
	v_mfma_f32_16x16x32_bf16 v[2:5], v[240:243], v[224:227], v[2:5]
	s_barrier
	s_add_i32 s39, s39, 2
	s_add_u32 s46, s46, 0x100
	s_addc_u32 s47, s47, 0
	s_add_u32 s12, s12, 0x100
	s_addc_u32 s13, s13, 0
	s_cmp_gt_u32 s39, 29
	s_cbranch_scc0 .LBB0_572
	s_cmp_lg_u32 s62, 0
	s_cbranch_scc0 .LBB0_575
	s_lshl_b32 s39, s61, 8
	s_mov_b64 s[12:13], 0
	s_branch .LBB0_576

.LBB0_788:
	s_add_u32 s39, s46, 0xfff80080
	s_addc_u32 s48, s47, -1
	s_add_i32 s64, 0, 0x10000
	v_add_u32_e32 v156, s64, v141
	ds_read_b128 v[144:147], v156
	ds_read_b128 v[148:151], v156 offset:1024
	ds_read_b128 v[152:155], v156 offset:2048
	ds_read_b128 v[168:171], v156 offset:3072
	s_cmp_eq_u32 s13, 28
	s_cselect_b32 s51, s43, s48
	s_cselect_b32 s50, s42, s39
	s_cselect_b32 s49, s45, s12
	s_cselect_b32 s48, s44, s1
	ds_read_b128 v[172:175], v143
	ds_read_b128 v[176:179], v143 offset:1024
	ds_read_b128 v[180:183], v143 offset:2048
	ds_read_b128 v[184:187], v143 offset:3072
	ds_read_b128 v[188:191], v143 offset:4096
	ds_read_b128 v[192:195], v143 offset:5120
	ds_read_b128 v[196:199], v143 offset:6144
	ds_read_b128 v[224:227], v143 offset:7168
	s_add_i32 m0, s54, 0xc000
	s_nop 0
	global_load_lds_dwordx4 v136, s[46:47]
	s_add_i32 m0, s54, 0xe000
	s_nop 0
	global_load_lds_dwordx4 v138, s[46:47]
	s_add_i32 s39, 0, 0x14000
	v_add_u32_e32 v156, s39, v141
	s_add_i32 s64, s64, s53
	ds_read_b128 v[228:231], v156
	ds_read_b128 v[232:235], v156 offset:1024
	ds_read_b128 v[236:239], v156 offset:2048
	ds_read_b128 v[240:243], v156 offset:3072
	s_waitcnt lgkmcnt(0)
	s_barrier
	v_mfma_f32_16x16x32_bf16 v[126:129], v[144:147], v[172:175], v[126:129]
	v_mfma_f32_16x16x32_bf16 v[122:125], v[152:155], v[172:175], v[122:125]
	v_mfma_f32_16x16x32_bf16 v[118:121], v[144:147], v[180:183], v[118:121]
	v_mfma_f32_16x16x32_bf16 v[114:117], v[152:155], v[180:183], v[114:117]
	v_mfma_f32_16x16x32_bf16 v[102:105], v[144:147], v[188:191], v[102:105]
	v_mfma_f32_16x16x32_bf16 v[98:101], v[152:155], v[188:191], v[98:101]
	v_mfma_f32_16x16x32_bf16 v[86:89], v[144:147], v[196:199], v[86:89]
	v_mfma_f32_16x16x32_bf16 v[82:85], v[152:155], v[196:199], v[82:85]
	v_mfma_f32_16x16x32_bf16 v[126:129], v[148:151], v[176:179], v[126:129]
	v_mfma_f32_16x16x32_bf16 v[122:125], v[168:171], v[176:179], v[122:125]
	v_mfma_f32_16x16x32_bf16 v[118:121], v[148:151], v[184:187], v[118:121]
	v_mfma_f32_16x16x32_bf16 v[114:117], v[168:171], v[184:187], v[114:117]
	v_mfma_f32_16x16x32_bf16 v[102:105], v[148:151], v[192:195], v[102:105]
	v_mfma_f32_16x16x32_bf16 v[98:101], v[168:171], v[192:195], v[98:101]
	v_mfma_f32_16x16x32_bf16 v[86:89], v[148:151], v[224:227], v[86:89]
	v_mfma_f32_16x16x32_bf16 v[82:85], v[168:171], v[224:227], v[82:85]
	v_mfma_f32_16x16x32_bf16 v[110:113], v[228:231], v[172:175], v[110:113]
	v_mfma_f32_16x16x32_bf16 v[106:109], v[236:239], v[172:175], v[106:109]
	v_mfma_f32_16x16x32_bf16 v[94:97], v[228:231], v[180:183], v[94:97]
	v_mfma_f32_16x16x32_bf16 v[90:93], v[236:239], v[180:183], v[90:93]
	v_mfma_f32_16x16x32_bf16 v[78:81], v[228:231], v[188:191], v[78:81]
	v_mfma_f32_16x16x32_bf16 v[74:77], v[236:239], v[188:191], v[74:77]
	v_mfma_f32_16x16x32_bf16 v[70:73], v[228:231], v[196:199], v[70:73]
	v_mfma_f32_16x16x32_bf16 v[66:69], v[236:239], v[196:199], v[66:69]
	v_mfma_f32_16x16x32_bf16 v[110:113], v[232:235], v[176:179], v[110:113]
	v_mfma_f32_16x16x32_bf16 v[106:109], v[240:243], v[176:179], v[106:109]
	v_mfma_f32_16x16x32_bf16 v[94:97], v[232:235], v[184:187], v[94:97]
	v_mfma_f32_16x16x32_bf16 v[90:93], v[240:243], v[184:187], v[90:93]
	v_mfma_f32_16x16x32_bf16 v[78:81], v[232:235], v[192:195], v[78:81]
	v_mfma_f32_16x16x32_bf16 v[74:77], v[240:243], v[192:195], v[74:77]
	v_mfma_f32_16x16x32_bf16 v[70:73], v[232:235], v[224:227], v[70:73]
	v_mfma_f32_16x16x32_bf16 v[66:69], v[240:243], v[224:227], v[66:69]
	s_barrier
	s_mov_b32 m0, s54
	s_add_u32 s78, s50, s94
	s_addc_u32 s79, s51, s95
	ds_read_b128 v[172:175], v143 offset:16384
	ds_read_b128 v[176:179], v143 offset:17408
	ds_read_b128 v[180:183], v143 offset:18432
	ds_read_b128 v[184:187], v143 offset:19456
	ds_read_b128 v[188:191], v143 offset:20480
	ds_read_b128 v[192:195], v143 offset:21504
	ds_read_b128 v[196:199], v143 offset:22528
	ds_read_b128 v[224:227], v143 offset:23552
	global_load_lds_dwordx4 v130, s[50:51]
	s_mov_b32 m0, s55
	s_nop 0
	global_load_lds_dwordx4 v132, s[50:51]
	s_add_u32 s76, s48, s94
	s_addc_u32 s77, s49, s95
	s_mov_b32 m0, s64
	s_nop 0
	global_load_lds_dwordx4 v0, s[48:49]
	s_add_i32 m0, s64, 0x2000
	s_nop 0
	global_load_lds_dwordx4 v134, s[48:49]
	s_add_u32 s64, s48, 0x80000
	s_addc_u32 s65, s49, 0
	s_add_i32 s39, s39, s53
	s_mov_b32 m0, s39
	s_nop 0
	global_load_lds_dwordx4 v0, s[64:65]
	s_add_i32 m0, s39, 0x2000
	s_nop 0
	global_load_lds_dwordx4 v134, s[64:65]
	s_waitcnt vmcnt(6) lgkmcnt(0)
	s_barrier
	v_mfma_f32_16x16x32_bf16 v[62:65], v[144:147], v[172:175], v[62:65]
	v_mfma_f32_16x16x32_bf16 v[58:61], v[152:155], v[172:175], v[58:61]
	v_mfma_f32_16x16x32_bf16 v[54:57], v[144:147], v[180:183], v[54:57]
	v_mfma_f32_16x16x32_bf16 v[50:53], v[152:155], v[180:183], v[50:53]
	v_mfma_f32_16x16x32_bf16 v[38:41], v[144:147], v[188:191], v[38:41]
	v_mfma_f32_16x16x32_bf16 v[34:37], v[152:155], v[188:191], v[34:37]
	v_mfma_f32_16x16x32_bf16 v[22:25], v[144:147], v[196:199], v[22:25]
	v_mfma_f32_16x16x32_bf16 v[18:21], v[152:155], v[196:199], v[18:21]
	v_mfma_f32_16x16x32_bf16 v[62:65], v[148:151], v[176:179], v[62:65]
	v_mfma_f32_16x16x32_bf16 v[58:61], v[168:171], v[176:179], v[58:61]
	v_mfma_f32_16x16x32_bf16 v[54:57], v[148:151], v[184:187], v[54:57]
	v_mfma_f32_16x16x32_bf16 v[50:53], v[168:171], v[184:187], v[50:53]
	v_mfma_f32_16x16x32_bf16 v[38:41], v[148:151], v[192:195], v[38:41]
	v_mfma_f32_16x16x32_bf16 v[34:37], v[168:171], v[192:195], v[34:37]
	v_mfma_f32_16x16x32_bf16 v[22:25], v[148:151], v[224:227], v[22:25]
	v_mfma_f32_16x16x32_bf16 v[18:21], v[168:171], v[224:227], v[18:21]
	v_mfma_f32_16x16x32_bf16 v[46:49], v[228:231], v[172:175], v[46:49]
	v_mfma_f32_16x16x32_bf16 v[42:45], v[236:239], v[172:175], v[42:45]
	v_mfma_f32_16x16x32_bf16 v[30:33], v[228:231], v[180:183], v[30:33]
	v_mfma_f32_16x16x32_bf16 v[26:29], v[236:239], v[180:183], v[26:29]
	v_mfma_f32_16x16x32_bf16 v[14:17], v[228:231], v[188:191], v[14:17]
	v_mfma_f32_16x16x32_bf16 v[10:13], v[236:239], v[188:191], v[10:13]
	v_mfma_f32_16x16x32_bf16 v[6:9], v[228:231], v[196:199], v[6:9]
	v_mfma_f32_16x16x32_bf16 v[2:5], v[236:239], v[196:199], v[2:5]
	v_mfma_f32_16x16x32_bf16 v[46:49], v[232:235], v[176:179], v[46:49]
	v_mfma_f32_16x16x32_bf16 v[42:45], v[240:243], v[176:179], v[42:45]
	v_mfma_f32_16x16x32_bf16 v[30:33], v[232:235], v[184:187], v[30:33]
	v_mfma_f32_16x16x32_bf16 v[26:29], v[240:243], v[184:187], v[26:29]
	v_mfma_f32_16x16x32_bf16 v[14:17], v[232:235], v[192:195], v[14:17]
	v_mfma_f32_16x16x32_bf16 v[10:13], v[240:243], v[192:195], v[10:13]
	v_mfma_f32_16x16x32_bf16 v[6:9], v[232:235], v[224:227], v[6:9]
	v_mfma_f32_16x16x32_bf16 v[2:5], v[240:243], v[224:227], v[2:5]
	s_barrier
	s_add_i32 s39, 0, 0x18000
	v_add_u32_e32 v161, s39, v141
	ds_read_b128 v[144:147], v161
	ds_read_b128 v[148:151], v161 offset:1024
	ds_read_b128 v[152:155], v161 offset:2048
	ds_read_b128 v[168:171], v161 offset:3072
	s_add_u32 s50, s50, 0x80000
	s_addc_u32 s51, s51, 0
	ds_read_b128 v[172:175], v143 offset:32768
	ds_read_b128 v[176:179], v143 offset:33792
	ds_read_b128 v[180:183], v143 offset:34816
	ds_read_b128 v[184:187], v143 offset:35840
	ds_read_b128 v[188:191], v143 offset:36864
	ds_read_b128 v[192:195], v143 offset:37888
	ds_read_b128 v[196:199], v143 offset:38912
	ds_read_b128 v[224:227], v143 offset:39936
	s_mov_b32 m0, s56
	s_nop 0
	global_load_lds_dwordx4 v130, s[50:51]
	s_mov_b32 m0, s57
	s_nop 0
	global_load_lds_dwordx4 v132, s[50:51]
	s_add_i32 s50, 0, 0x1c000
	s_add_i32 s39, s39, s53
	v_add_u32_e32 v161, s50, v141
	ds_read_b128 v[228:231], v161
	ds_read_b128 v[232:235], v161 offset:1024
	ds_read_b128 v[236:239], v161 offset:2048
	ds_read_b128 v[240:243], v161 offset:3072
	s_waitcnt lgkmcnt(0)
	s_barrier
	v_mfma_f32_16x16x32_bf16 v[126:129], v[144:147], v[172:175], v[126:129]
	v_mfma_f32_16x16x32_bf16 v[122:125], v[152:155], v[172:175], v[122:125]
	v_mfma_f32_16x16x32_bf16 v[118:121], v[144:147], v[180:183], v[118:121]
	v_mfma_f32_16x16x32_bf16 v[114:117], v[152:155], v[180:183], v[114:117]
	v_mfma_f32_16x16x32_bf16 v[102:105], v[144:147], v[188:191], v[102:105]
	v_mfma_f32_16x16x32_bf16 v[98:101], v[152:155], v[188:191], v[98:101]
	v_mfma_f32_16x16x32_bf16 v[86:89], v[144:147], v[196:199], v[86:89]
	v_mfma_f32_16x16x32_bf16 v[82:85], v[152:155], v[196:199], v[82:85]
	v_mfma_f32_16x16x32_bf16 v[126:129], v[148:151], v[176:179], v[126:129]
	v_mfma_f32_16x16x32_bf16 v[122:125], v[168:171], v[176:179], v[122:125]
	v_mfma_f32_16x16x32_bf16 v[118:121], v[148:151], v[184:187], v[118:121]
	v_mfma_f32_16x16x32_bf16 v[114:117], v[168:171], v[184:187], v[114:117]
	v_mfma_f32_16x16x32_bf16 v[102:105], v[148:151], v[192:195], v[102:105]
	v_mfma_f32_16x16x32_bf16 v[98:101], v[168:171], v[192:195], v[98:101]
	v_mfma_f32_16x16x32_bf16 v[86:89], v[148:151], v[224:227], v[86:89]
	v_mfma_f32_16x16x32_bf16 v[82:85], v[168:171], v[224:227], v[82:85]
	v_mfma_f32_16x16x32_bf16 v[110:113], v[228:231], v[172:175], v[110:113]
	v_mfma_f32_16x16x32_bf16 v[106:109], v[236:239], v[172:175], v[106:109]
	v_mfma_f32_16x16x32_bf16 v[94:97], v[228:231], v[180:183], v[94:97]
	v_mfma_f32_16x16x32_bf16 v[90:93], v[236:239], v[180:183], v[90:93]
	v_mfma_f32_16x16x32_bf16 v[78:81], v[228:231], v[188:191], v[78:81]
	v_mfma_f32_16x16x32_bf16 v[74:77], v[236:239], v[188:191], v[74:77]
	v_mfma_f32_16x16x32_bf16 v[70:73], v[228:231], v[196:199], v[70:73]
	v_mfma_f32_16x16x32_bf16 v[66:69], v[236:239], v[196:199], v[66:69]
	v_mfma_f32_16x16x32_bf16 v[110:113], v[232:235], v[176:179], v[110:113]
	v_mfma_f32_16x16x32_bf16 v[106:109], v[240:243], v[176:179], v[106:109]
	v_mfma_f32_16x16x32_bf16 v[94:97], v[232:235], v[184:187], v[94:97]
	v_mfma_f32_16x16x32_bf16 v[90:93], v[240:243], v[184:187], v[90:93]
	v_mfma_f32_16x16x32_bf16 v[78:81], v[232:235], v[192:195], v[78:81]
	v_mfma_f32_16x16x32_bf16 v[74:77], v[240:243], v[192:195], v[74:77]
	v_mfma_f32_16x16x32_bf16 v[70:73], v[232:235], v[224:227], v[70:73]
	v_mfma_f32_16x16x32_bf16 v[66:69], v[240:243], v[224:227], v[66:69]
	s_barrier
	s_mov_b32 m0, s59
	ds_read_b128 v[172:175], v143 offset:49152
	ds_read_b128 v[176:179], v143 offset:50176
	ds_read_b128 v[180:183], v143 offset:51200
	ds_read_b128 v[184:187], v143 offset:52224
	ds_read_b128 v[188:191], v143 offset:53248
	ds_read_b128 v[192:195], v143 offset:54272
	ds_read_b128 v[196:199], v143 offset:55296
	ds_read_b128 v[224:227], v143 offset:56320
	global_load_lds_dwordx4 v130, s[78:79]
	s_mov_b32 m0, s61
	s_nop 0
	global_load_lds_dwordx4 v132, s[78:79]
	s_mov_b32 m0, s39
	s_nop 0
	global_load_lds_dwordx4 v0, s[76:77]
	s_add_i32 m0, s39, 0x2000
	s_nop 0
	global_load_lds_dwordx4 v134, s[76:77]
	s_add_u32 s48, s48, 0x80080
	s_addc_u32 s49, s49, 0
	s_add_i32 s39, s50, s53
	s_mov_b32 m0, s39
	s_nop 0
	global_load_lds_dwordx4 v0, s[48:49]
	s_add_i32 m0, s39, 0x2000
	s_nop 0
	global_load_lds_dwordx4 v134, s[48:49]
	s_waitcnt vmcnt(6) lgkmcnt(0)
	s_barrier
	v_mfma_f32_16x16x32_bf16 v[62:65], v[144:147], v[172:175], v[62:65]
	v_mfma_f32_16x16x32_bf16 v[58:61], v[152:155], v[172:175], v[58:61]
	v_mfma_f32_16x16x32_bf16 v[54:57], v[144:147], v[180:183], v[54:57]
	v_mfma_f32_16x16x32_bf16 v[50:53], v[152:155], v[180:183], v[50:53]
	v_mfma_f32_16x16x32_bf16 v[38:41], v[144:147], v[188:191], v[38:41]
	v_mfma_f32_16x16x32_bf16 v[34:37], v[152:155], v[188:191], v[34:37]
	v_mfma_f32_16x16x32_bf16 v[22:25], v[144:147], v[196:199], v[22:25]
	v_mfma_f32_16x16x32_bf16 v[18:21], v[152:155], v[196:199], v[18:21]
	v_mfma_f32_16x16x32_bf16 v[62:65], v[148:151], v[176:179], v[62:65]
	v_mfma_f32_16x16x32_bf16 v[58:61], v[168:171], v[176:179], v[58:61]
	v_mfma_f32_16x16x32_bf16 v[54:57], v[148:151], v[184:187], v[54:57]
	v_mfma_f32_16x16x32_bf16 v[50:53], v[168:171], v[184:187], v[50:53]
	v_mfma_f32_16x16x32_bf16 v[38:41], v[148:151], v[192:195], v[38:41]
	v_mfma_f32_16x16x32_bf16 v[34:37], v[168:171], v[192:195], v[34:37]
	v_mfma_f32_16x16x32_bf16 v[22:25], v[148:151], v[224:227], v[22:25]
	v_mfma_f32_16x16x32_bf16 v[18:21], v[168:171], v[224:227], v[18:21]
	v_mfma_f32_16x16x32_bf16 v[46:49], v[228:231], v[172:175], v[46:49]
	v_mfma_f32_16x16x32_bf16 v[42:45], v[236:239], v[172:175], v[42:45]
	v_mfma_f32_16x16x32_bf16 v[30:33], v[228:231], v[180:183], v[30:33]
	v_mfma_f32_16x16x32_bf16 v[26:29], v[236:239], v[180:183], v[26:29]
	v_mfma_f32_16x16x32_bf16 v[14:17], v[228:231], v[188:191], v[14:17]
	v_mfma_f32_16x16x32_bf16 v[10:13], v[236:239], v[188:191], v[10:13]
	v_mfma_f32_16x16x32_bf16 v[6:9], v[228:231], v[196:199], v[6:9]
	v_mfma_f32_16x16x32_bf16 v[2:5], v[236:239], v[196:199], v[2:5]
	v_mfma_f32_16x16x32_bf16 v[46:49], v[232:235], v[176:179], v[46:49]
	v_mfma_f32_16x16x32_bf16 v[42:45], v[240:243], v[176:179], v[42:45]
	v_mfma_f32_16x16x32_bf16 v[30:33], v[232:235], v[184:187], v[30:33]
	v_mfma_f32_16x16x32_bf16 v[26:29], v[240:243], v[184:187], v[26:29]
	v_mfma_f32_16x16x32_bf16 v[14:17], v[232:235], v[192:195], v[14:17]
	v_mfma_f32_16x16x32_bf16 v[10:13], v[240:243], v[192:195], v[10:13]
	v_mfma_f32_16x16x32_bf16 v[6:9], v[232:235], v[224:227], v[6:9]
	v_mfma_f32_16x16x32_bf16 v[2:5], v[240:243], v[224:227], v[2:5]
	s_barrier
	s_add_i32 s13, s13, 2
	s_add_u32 s46, s46, 0x100
	s_addc_u32 s47, s47, 0
	s_add_u32 s1, s1, 0x100
	s_addc_u32 s12, s12, 0
	s_cmp_gt_u32 s13, 29
	s_cbranch_scc0 .LBB0_788
	s_cmp_lg_u32 s62, 0
	s_cbranch_scc0 .LBB0_791
	s_lshl_b32 s1, s60, 8
	s_mov_b64 s[12:13], 0
	s_branch .LBB0_792
